# GEMM phase prologues: K-tile 1's 6 LDS-DMA loads issued together with K-tile 0's 8 (first wait vmcnt(2)->vmcnt(8)), one load round trip less per GEMM phase
# baseline (speedup 1.0000x reference)
;     __host__ __device__ bool next(int i, Unit& u) const {
;         const long L = (long)i * G + c; if (L >= nwg) return false;
;         int wgid = (int)L; { const int q = nwg / NXCD, r = nwg % NXCD, xcd = wgid % NXCD, off = wgid / NXCD; wgid = (xcd < r ? xcd * (q + 1) : r * (q + 1) + (xcd - r) * q) + off; }
;         const int nig = WGM * nN, gid = wgid / nig, fm = gid * WGM, gsz = (nM - fm) < WGM ? (nM - fm) : WGM;
; template <class Epi, class Sched, bool ALIGN_EPI = false, bool SP2 = false>
; __device__ __forceinline__ void gemm_phase(PG8_LAS unsigned char* lds, const Gemm g, const Sched& S, const Epi& E) {
;     const int tid = threadIdx.x, wid = __builtin_amdgcn_readfirstlane(tid >> 6), lane = tid & 63, wr = wid >> 2, wc = wid & 3, fr = lane & 15, fq = lane >> 4;
;     const int K = g.K, nt = K / BK;
;     unsigned voffA[2], voffB[2];
; #pragma unroll
;     for (int i = 0; i < 2; ++i) { int R, C; stage_rc(tid * 16 + i * 8192, R, C); const int Rb = Epi::PERM ? ((R & ~31) + perm32(R & 31)) : R;
;         voffA[i] = (unsigned)(R * K + C) * 2u; voffB[i] = (unsigned)(Rb * K + C) * 2u; }
;     const size_t kstep = (size_t)(BK * 2);
;     const size_t hstep = (size_t)HALF * K * 2;
;     const size_t tstep = 2 * hstep;
;     const unsigned ldsw = (unsigned)wid * 1024u;
;     const int aoff = lds_byte(wr * 64 + fr, fq * 8), boff = lds_byte(wc * 32 + fr, fq * 8);
;     ...
;     Unit cur, nxt; int ui = 0;
;     if (!S.next(0, cur)) return;
;     f32x4 acc[2][2][4][2];
; #pragma unroll
;     for (int a = 0; a < 2; ++a)
; #pragma unroll
;         for (int b = 0; b < 2; ++b)
; #pragma unroll
;             for (int m = 0; m < 4; ++m)
; #pragma unroll
;                 for (int n = 0; n < 2; ++n) acc[a][b][m][n] = (f32x4){0.f, 0.f, 0.f, 0.f};
;     bf16x8 At[4][2], B0[2][2], B1[2][2];
;     const char* cA = (const char*)g.A + (size_t)cur.pm * tstep; const char* cB = (const char*)g.Bt + (size_t)cur.pn * tstep;
;     S.a_ready(cur);
;     if constexpr (SP2) {
;         PG8_STAGE(PG8_SB(0, 0), cB, voffB); PG8_STAGE(PG8_SB(0, 1), cB + hstep, voffB); PG8_STAGE(PG8_SA(0, 0), cA, voffA); PG8_STAGE(PG8_SA(0, 1), cA + hstep, voffA);
;         if (wr == 1) PG8_BAR;
;         PG8_WAIT_V(2); PG8_BAR;
;         PG8_STAGE(PG8_SB(1, 0), cB + kstep, voffB); PG8_STAGE(PG8_SA(1, 0), cA + kstep, voffA); PG8_STAGE(PG8_SB(1, 1), cB + hstep + kstep, voffB);
;         PG8_WAIT_V(6); PG8_BAR;
.LBB0_371:
	s_cmp_lt_i32 s30, 3
	s_cselect_b64 s[4:5], -1, 0
	s_and_b64 s[4:5], s[4:5], s[0:1]
	s_andn2_b64 vcc, exec, s[4:5]
	s_cbranch_vccnz .LBB0_388
	s_cmpk_gt_i32 s2, 0x62f
	v_readfirstlane_b32 s1, v152
	s_cbranch_scc1 .LBB0_388
	v_lshrrev_b32_e32 v2, 1, v152
	v_and_b32_e32 v11, 24, v2
	v_lshrrev_b32_e32 v2, 5, v152
	v_and_b32_e32 v2, 4, v2
	v_bfe_u32 v3, v152, 2, 2
	v_lshlrev_b32_e32 v0, 4, v152
	v_and_b32_e32 v1, 32, v152
	v_bfe_u32 v10, v152, 2, 4
	v_or3_b32 v2, v2, v3, v11
	v_lshrrev_b32_e32 v3, 3, v152
	s_movk_i32 s0, 0x70
	v_bitop3_b32 v8, v0, v1, 48 bitop3:0x6c
	v_and_b32_e32 v9, 64, v152
	v_and_or_b32 v4, v3, s0, v10
	s_movk_i32 s0, 0x60
	v_add_u32_e32 v12, 0x2000, v0
	s_add_u32 s52, s28, 0x600000
	v_or_b32_e32 v1, v8, v9
	v_and_or_b32 v3, v3, s0, v2
	v_lshrrev_b32_e32 v0, 7, v12
	s_movk_i32 s0, 0xf0
	s_addc_u32 s53, s29, 0
	v_lshl_or_b32 v130, v3, 11, v1
	v_and_or_b32 v3, v0, s0, v10
	s_movk_i32 s0, 0xe0
	s_ashr_i32 s55, s2, 31
	v_and_or_b32 v0, v0, s0, v2
	s_lshr_b32 s0, s55, 29
	s_add_i32 s0, s2, s0
	s_lshr_b32 s10, s1, 6
	s_ashr_i32 s6, s0, 3
	s_and_b32 s0, s0, -8
	s_lshr_b32 s12, s1, 8
	s_lshl_b32 s54, s10, 10
	s_sub_i32 s0, s2, s0
	s_cmp_lt_i32 s0, 0
	s_movk_i32 s62, 0xc7
	s_cselect_b32 s7, s62, 0xc6
	s_mul_i32 s0, s0, s7
	s_add_i32 s0, s0, s6
	s_mul_hi_i32 s6, s0, 0x2aaaaaab
	s_lshr_b32 s7, s6, 31
	s_ashr_i32 s6, s6, 3
	s_add_i32 s6, s6, s7
	s_lshl_b32 s7, s6, 3
	s_mul_i32 s6, s6, 48
	s_sub_i32 s6, s0, s6
	s_bfe_i32 s0, s6, 0x80000
	s_bfe_u32 s0, s0, 0x3000c
	s_add_i32 s8, s6, s0
	s_bfe_i32 s0, s8, 0x80000
	s_and_b32 s8, s8, 0xf8
	s_sub_i32 s6, s6, s8
	s_sext_i32_i16 s0, s0
	s_sext_i32_i8 s6, s6
	s_lshr_b32 s0, s0, 3
	s_add_i32 s40, s7, s6
	s_ashr_i32 s41, s40, 31
	s_bfe_i64 s[8:9], s[0:1], 0x100000
	s_lshl_b64 s[6:7], s[40:41], 19
	s_lshl_b64 s[8:9], s[8:9], 19
	s_add_u32 s44, s52, s8
	s_addc_u32 s45, s53, s9
	s_add_i32 s41, s54, 0
	s_add_i32 m0, s41, 0x10000
	v_lshl_or_b32 v134, v0, 11, v1
	global_load_lds_dwordx4 v130, s[44:45]
	s_add_i32 m0, s41, 0x12000
	s_add_u32 s8, s44, 0x40000
	global_load_lds_dwordx4 v134, s[44:45]
	s_addc_u32 s9, s45, 0
	s_add_i32 m0, s41, 0x14000
	v_lshl_or_b32 v128, v4, 11, v1
	global_load_lds_dwordx4 v130, s[8:9]
	s_add_i32 m0, s41, 0x16000
	s_add_u32 s42, s16, s6
	s_addc_u32 s43, s17, s7
	s_add_i32 s63, s41, 0x2000
	global_load_lds_dwordx4 v134, s[8:9]
	s_mov_b32 m0, s41
	s_add_u32 s6, s42, 0x40000
	v_lshl_or_b32 v132, v3, 11, v1
	global_load_lds_dwordx4 v128, s[42:43]
	s_mov_b32 m0, s63
	s_addc_u32 s7, s43, 0
	s_add_i32 s70, s41, 0x4000
	global_load_lds_dwordx4 v132, s[42:43]
	s_mov_b32 m0, s70
	s_add_i32 s71, s41, 0x6000
	global_load_lds_dwordx4 v128, s[6:7]
	s_mov_b32 m0, s71
	v_mov_b32_e32 v131, 0
	global_load_lds_dwordx4 v132, s[6:7]
	v_mov_b32_e32 v135, v131
	v_mov_b32_e32 v129, v131
	v_mov_b32_e32 v133, v131
	s_cmp_eq_u32 s12, 1
	s_mov_b32 s72, 0
	v_lshl_add_u64 v[6:7], s[44:45], 0, v[130:131]
	v_lshl_add_u64 v[4:5], s[44:45], 0, v[134:135]
	v_lshl_add_u64 v[0:1], s[42:43], 0, v[128:129]
	s_cselect_b64 s[6:7], -1, 0
	s_cmp_lg_u32 s12, 1
	v_lshl_add_u64 v[2:3], s[42:43], 0, v[132:133]
	s_add_u32 s8, s28, 0xfa00000
	s_addc_u32 s9, s29, 0
	s_lshl_b32 s10, s10, 5
	s_and_b32 s22, s10, 0x60
	s_mov_b64 s[10:11], 0x80
	s_add_i32 m0, s41, 0x18000
	v_lshl_add_u64 v[6:7], v[6:7], 0, s[10:11]
	s_ashr_i32 s73, s3, 31
	s_lshl_b32 s13, s12, 13
	s_lshl_b32 s23, s22, 7
	global_load_lds_dwordx4 v[6:7], off
	v_lshl_add_u64 v[4:5], v[4:5], 0, s[10:11]
	s_add_i32 m0, s41, 0x1a000
	s_add_i32 s74, s41, 0x8000
	s_add_i32 s75, s41, 0xa000
	global_load_lds_dwordx4 v[4:5], off
	v_lshl_add_u64 v[0:1], v[0:1], 0, s[10:11]
	s_mov_b32 m0, s74
	s_add_u32 s20, s44, 0x40080
	global_load_lds_dwordx4 v[0:1], off
	v_lshl_add_u64 v[0:1], v[2:3], 0, s[10:11]
	s_mov_b32 m0, s75
	s_addc_u32 s21, s45, 0
	global_load_lds_dwordx4 v[0:1], off
	s_add_i32 m0, s41, 0x1c000
	v_lshl_add_u64 v[0:1], s[20:21], 0, v[130:131]
	global_load_lds_dwordx4 v[0:1], off
	v_lshl_add_u64 v[0:1], s[20:21], 0, v[134:135]
	s_add_i32 m0, s41, 0x1e000
	s_sext_i32_i8 s79, s0
	global_load_lds_dwordx4 v[0:1], off
	s_cmp_lg_u32 s12, 1
	s_cbranch_scc1 .LBB0_375
	s_barrier
.LBB0_375:
	s_waitcnt vmcnt(8)
	s_barrier
	v_and_b32_e32 v0, 15, v152
	v_lshlrev_b32_e32 v1, 1, v11
	v_lshlrev_b32_e32 v2, 6, v152
	s_movk_i32 s0, 0x3c0
	v_lshlrev_b32_e32 v3, 2, v152
	v_and_or_b32 v2, v2, s0, v1
	v_and_b32_e32 v3, 32, v3
	v_lshl_or_b32 v148, s12, 6, v0
	v_lshl_or_b32 v0, v0, 6, v1
	v_lshlrev_b32_e32 v1, 8, v152
	v_bitop3_b32 v149, s23, v2, v3 bitop3:0xf6
	v_and_b32_e32 v1, 0x38000, v1
	v_lshlrev_b32_e32 v2, 11, v10
	v_or3_b32 v1, v8, v1, v2
	v_add_u32_e32 v136, v1, v9
	v_lshlrev_b32_e32 v1, 4, v12
	s_waitcnt vmcnt(6)
	s_cmpk_lt_u32 s1, 0x100
	v_and_b32_e32 v1, 0x78000, v1
	v_bitop3_b32 v0, v0, s13, v3 bitop3:0xde
	s_cselect_b64 s[12:13], -1, 0
	v_or3_b32 v1, v8, v1, v2
	s_add_i32 s76, 0, 0x10000
	s_add_i32 s77, 0, 0x14000
	v_or_b32_e32 v150, s22, v11
	v_mov_b32_e32 v137, v131
	v_add_u32_e32 v138, v1, v9
	v_mov_b32_e32 v139, v131
	v_mov_b64_e32 v[140:141], 0x630
	v_mov_b64_e32 v[142:143], 0x62f
	v_add_u32_e32 v151, s76, v149
	v_add_u32_e32 v153, s77, v149
	v_add_u32_e32 v154, 0, v0
	s_movk_i32 s78, 0xc00
	s_barrier
	s_mov_b32 s60, 0
	s_branch .LBB0_378

;     __host__ __device__ bool next(int i, Unit& u) const {
;         const long L = (long)i * G + c; if (L >= nwg) return false;
;         int wgid = (int)L; { const int q = nwg / NXCD, r = nwg % NXCD, xcd = wgid % NXCD, off = wgid / NXCD; wgid = (xcd < r ? xcd * (q + 1) : r * (q + 1) + (xcd - r) * q) + off; }
;         const int nig = WGM * nN, gid = wgid / nig, fm = gid * WGM, gsz = (nM - fm) < WGM ? (nM - fm) : WGM;
; template <class Epi, class Sched, bool ALIGN_EPI = false, bool SP2 = false>
; __device__ __forceinline__ void gemm_phase(PG8_LAS unsigned char* lds, const Gemm g, const Sched& S, const Epi& E) {
;     const int tid = threadIdx.x, wid = __builtin_amdgcn_readfirstlane(tid >> 6), lane = tid & 63, wr = wid >> 2, wc = wid & 3, fr = lane & 15, fq = lane >> 4;
;     const int K = g.K, nt = K / BK;
;     unsigned voffA[2], voffB[2];
; #pragma unroll
;     for (int i = 0; i < 2; ++i) { int R, C; stage_rc(tid * 16 + i * 8192, R, C); const int Rb = Epi::PERM ? ((R & ~31) + perm32(R & 31)) : R;
;         voffA[i] = (unsigned)(R * K + C) * 2u; voffB[i] = (unsigned)(Rb * K + C) * 2u; }
;     const size_t kstep = (size_t)(BK * 2);
;     const size_t hstep = (size_t)HALF * K * 2;
;     const size_t tstep = 2 * hstep;
;     const unsigned ldsw = (unsigned)wid * 1024u;
;     const int aoff = lds_byte(wr * 64 + fr, fq * 8), boff = lds_byte(wc * 32 + fr, fq * 8);
;     ...
;     Unit cur, nxt; int ui = 0;
;     if (!S.next(0, cur)) return;
;     f32x4 acc[2][2][4][2];
; #pragma unroll
;     for (int a = 0; a < 2; ++a)
; #pragma unroll
;         for (int b = 0; b < 2; ++b)
; #pragma unroll
;             for (int m = 0; m < 4; ++m)
; #pragma unroll
;                 for (int n = 0; n < 2; ++n) acc[a][b][m][n] = (f32x4){0.f, 0.f, 0.f, 0.f};
;     bf16x8 At[4][2], B0[2][2], B1[2][2];
;     const char* cA = (const char*)g.A + (size_t)cur.pm * tstep; const char* cB = (const char*)g.Bt + (size_t)cur.pn * tstep;
;     S.a_ready(cur);
;     if constexpr (SP2) {
;         PG8_STAGE(PG8_SB(0, 0), cB, voffB); PG8_STAGE(PG8_SB(0, 1), cB + hstep, voffB); PG8_STAGE(PG8_SA(0, 0), cA, voffA); PG8_STAGE(PG8_SA(0, 1), cA + hstep, voffA);
;         if (wr == 1) PG8_BAR;
;         PG8_WAIT_V(2); PG8_BAR;
;         PG8_STAGE(PG8_SB(1, 0), cB + kstep, voffB); PG8_STAGE(PG8_SA(1, 0), cA + kstep, voffA); PG8_STAGE(PG8_SB(1, 1), cB + hstep + kstep, voffB);
;         PG8_WAIT_V(6); PG8_BAR;
.LBB0_576:
	s_cmp_lt_i32 s30, 6
	s_cselect_b64 s[0:1], -1, 0
	s_and_b64 s[4:5], s[0:1], s[4:5]
	s_andn2_b64 vcc, exec, s[4:5]
	s_cbranch_vccnz .LBB0_597
	s_cmpk_gt_i32 s2, 0x3ff
	v_readfirstlane_b32 s1, v152
	s_cbranch_scc1 .LBB0_597
	v_lshrrev_b32_e32 v2, 1, v152
	v_and_b32_e32 v11, 24, v2
	v_lshrrev_b32_e32 v2, 5, v152
	v_and_b32_e32 v2, 4, v2
	v_bfe_u32 v3, v152, 2, 2
	s_add_u32 s60, s28, 0x1c000000
	v_lshlrev_b32_e32 v0, 4, v152
	v_and_b32_e32 v1, 32, v152
	v_bfe_u32 v10, v152, 2, 4
	v_or3_b32 v2, v2, v3, v11
	v_lshrrev_b32_e32 v3, 3, v152
	s_movk_i32 s0, 0x70
	s_addc_u32 s61, s29, 0
	v_bitop3_b32 v8, v0, v1, 48 bitop3:0x6c
	v_and_b32_e32 v9, 64, v152
	v_and_or_b32 v4, v3, s0, v10
	s_movk_i32 s0, 0x60
	v_add_u32_e32 v12, 0x2000, v0
	s_add_u32 s62, s28, 0x900000
	v_or_b32_e32 v1, v8, v9
	v_and_or_b32 v3, v3, s0, v2
	v_lshrrev_b32_e32 v0, 7, v12
	s_movk_i32 s0, 0xf0
	s_addc_u32 s63, s29, 0
	s_waitcnt vmcnt(0)
	v_lshl_or_b32 v138, v3, 11, v1
	v_and_or_b32 v3, v0, s0, v10
	s_movk_i32 s0, 0xe0
	s_ashr_i32 s71, s2, 31
	v_and_or_b32 v0, v0, s0, v2
	s_lshr_b32 s0, s71, 29
	s_add_i32 s0, s2, s0
	s_and_b32 s6, s0, -8
	s_lshr_b32 s10, s1, 6
	s_sub_i32 s6, s2, s6
	s_lshr_b32 s12, s1, 8
	s_lshl_b32 s70, s10, 10
	s_lshl_b32 s8, s6, 7
	s_ashr_i32 s0, s0, 3
	s_mul_i32 s7, s6, 0x81
	s_cmp_lt_i32 s6, 0
	s_cselect_b32 s6, s7, s8
	s_add_i32 s0, s6, s0
	s_ashr_i32 s6, s0, 31
	s_lshr_b32 s6, s6, 27
	s_add_i32 s6, s0, s6
	s_ashr_i32 s7, s6, 5
	s_andn2_b32 s6, s6, 31
	s_sub_i32 s6, s0, s6
	s_bfe_i32 s0, s6, 0x80000
	s_bfe_u32 s0, s0, 0x3000c
	s_add_i32 s8, s6, s0
	s_bfe_i32 s0, s8, 0x80000
	s_and_b32 s8, s8, 0xf8
	s_sub_i32 s6, s6, s8
	s_lshl_b32 s7, s7, 3
	s_sext_i32_i16 s0, s0
	s_sext_i32_i8 s6, s6
	s_lshr_b32 s0, s0, 3
	s_add_i32 s52, s7, s6
	s_ashr_i32 s53, s52, 31
	s_bfe_i64 s[8:9], s[0:1], 0x100000
	s_lshl_b64 s[6:7], s[52:53], 19
	s_lshl_b64 s[8:9], s[8:9], 19
	s_add_u32 s56, s62, s8
	s_addc_u32 s57, s63, s9
	s_add_i32 s53, s70, 0
	s_add_i32 m0, s53, 0x10000
	v_lshl_or_b32 v142, v0, 11, v1
	global_load_lds_dwordx4 v138, s[56:57]
	s_add_i32 m0, s53, 0x12000
	s_add_u32 s8, s56, 0x40000
	global_load_lds_dwordx4 v142, s[56:57]
	s_addc_u32 s9, s57, 0
	s_add_i32 m0, s53, 0x14000
	v_lshl_or_b32 v136, v4, 11, v1
	global_load_lds_dwordx4 v138, s[8:9]
	s_add_i32 m0, s53, 0x16000
	s_add_u32 s54, s60, s6
	s_addc_u32 s55, s61, s7
	s_add_i32 s72, s53, 0x2000
	global_load_lds_dwordx4 v142, s[8:9]
	s_mov_b32 m0, s53
	s_add_u32 s6, s54, 0x40000
	v_lshl_or_b32 v140, v3, 11, v1
	global_load_lds_dwordx4 v136, s[54:55]
	s_mov_b32 m0, s72
	s_addc_u32 s7, s55, 0
	s_add_i32 s73, s53, 0x4000
	global_load_lds_dwordx4 v140, s[54:55]
	s_mov_b32 m0, s73
	s_add_i32 s74, s53, 0x6000
	global_load_lds_dwordx4 v136, s[6:7]
	s_mov_b32 m0, s74
	v_mov_b32_e32 v139, 0
	global_load_lds_dwordx4 v140, s[6:7]
	v_mov_b32_e32 v143, v139
	v_mov_b32_e32 v137, v139
	v_mov_b32_e32 v141, v139
	s_cmp_eq_u32 s12, 1
	s_mov_b32 s75, 0
	v_lshl_add_u64 v[6:7], s[56:57], 0, v[138:139]
	v_lshl_add_u64 v[4:5], s[56:57], 0, v[142:143]
	v_lshl_add_u64 v[0:1], s[54:55], 0, v[136:137]
	s_cselect_b64 s[6:7], -1, 0
	s_cmp_lg_u32 s12, 1
	v_lshl_add_u64 v[2:3], s[54:55], 0, v[140:141]
	s_add_u32 s8, s28, 0x2fa00000
	s_addc_u32 s9, s29, 0
	s_add_u32 s76, s28, 0x2000
	s_addc_u32 s77, s29, 0
	s_lshl_b32 s10, s10, 5
	s_and_b32 s22, s10, 0x60
	s_mov_b64 s[10:11], 0x80
	s_add_i32 m0, s53, 0x18000
	v_lshl_add_u64 v[6:7], v[6:7], 0, s[10:11]
	s_ashr_i32 s78, s3, 31
	s_lshl_b32 s13, s12, 13
	s_lshl_b32 s23, s22, 7
	global_load_lds_dwordx4 v[6:7], off
	v_lshl_add_u64 v[4:5], v[4:5], 0, s[10:11]
	s_add_i32 m0, s53, 0x1a000
	s_add_i32 s79, s53, 0x8000
	s_add_i32 s80, s53, 0xa000
	global_load_lds_dwordx4 v[4:5], off
	v_lshl_add_u64 v[0:1], v[0:1], 0, s[10:11]
	s_mov_b32 m0, s79
	s_add_u32 s20, s56, 0x40080
	global_load_lds_dwordx4 v[0:1], off
	v_lshl_add_u64 v[0:1], v[2:3], 0, s[10:11]
	s_mov_b32 m0, s80
	s_addc_u32 s21, s57, 0
	global_load_lds_dwordx4 v[0:1], off
	s_add_i32 m0, s53, 0x1c000
	v_lshl_add_u64 v[0:1], s[20:21], 0, v[138:139]
	global_load_lds_dwordx4 v[0:1], off
	v_lshl_add_u64 v[0:1], s[20:21], 0, v[142:143]
	s_add_i32 m0, s53, 0x1e000
	s_sext_i32_i8 s83, s0
	global_load_lds_dwordx4 v[0:1], off
	s_cmp_lg_u32 s12, 1
	s_cbranch_scc1 .LBB0_580
	s_barrier
.LBB0_580:
	s_waitcnt vmcnt(8)
	s_barrier
	v_and_b32_e32 v0, 15, v152
	v_lshlrev_b32_e32 v1, 1, v11
	v_lshlrev_b32_e32 v2, 6, v152
	s_movk_i32 s0, 0x3c0
	v_lshlrev_b32_e32 v3, 2, v152
	v_and_or_b32 v2, v2, s0, v1
	v_and_b32_e32 v3, 32, v3
	v_lshl_or_b32 v162, s12, 6, v0
	v_lshl_or_b32 v0, v0, 6, v1
	v_lshlrev_b32_e32 v1, 8, v152
	v_bitop3_b32 v163, s23, v2, v3 bitop3:0xf6
	v_and_b32_e32 v1, 0x38000, v1
	v_lshlrev_b32_e32 v2, 11, v10
	v_or3_b32 v1, v8, v1, v2
	v_add_u32_e32 v144, v1, v9
	v_lshlrev_b32_e32 v1, 4, v12
	s_waitcnt vmcnt(6)
	s_cmpk_lt_u32 s1, 0x100
	v_and_b32_e32 v1, 0x78000, v1
	v_bitop3_b32 v0, v0, s13, v3 bitop3:0xde
	s_cselect_b64 s[12:13], -1, 0
	v_or3_b32 v1, v8, v1, v2
	s_add_i32 s81, 0, 0x10000
	s_add_i32 s82, 0, 0x14000
	v_or_b32_e32 v164, s22, v11
	v_mov_b32_e32 v145, v139
	v_add_u32_e32 v146, v1, v9
	v_mov_b32_e32 v147, v139
	v_mov_b64_e32 v[148:149], 0x400
	v_mov_b64_e32 v[150:151], 0x3ff
	v_add_u32_e32 v165, s81, v163
	v_add_u32_e32 v166, s82, v163
	v_add_u32_e32 v167, 0, v0
	s_mov_b64 s[20:21], 0x20000
	s_mov_b64 s[22:23], 0x24000
	s_mov_b64 s[24:25], 0x28000
	s_mov_b64 s[38:39], 0x2c000
	s_barrier
	s_branch .LBB0_583

;     __host__ __device__ bool next(int i, Unit& u) const {
;         const long L = (long)i * G + c; if (L >= nwg) return false;
;         int wgid = (int)L; { const int q = nwg / NXCD, r = nwg % NXCD, xcd = wgid % NXCD, off = wgid / NXCD; wgid = (xcd < r ? xcd * (q + 1) : r * (q + 1) + (xcd - r) * q) + off; }
;         const int nig = WGM * nN, gid = wgid / nig, fm = gid * WGM, gsz = (nM - fm) < WGM ? (nM - fm) : WGM;
; template <class Epi, class Sched, bool ALIGN_EPI = false, bool SP2 = false>
; __device__ __forceinline__ void gemm_phase(PG8_LAS unsigned char* lds, const Gemm g, const Sched& S, const Epi& E) {
;     const int tid = threadIdx.x, wid = __builtin_amdgcn_readfirstlane(tid >> 6), lane = tid & 63, wr = wid >> 2, wc = wid & 3, fr = lane & 15, fq = lane >> 4;
;     const int K = g.K, nt = K / BK;
;     unsigned voffA[2], voffB[2];
; #pragma unroll
;     for (int i = 0; i < 2; ++i) { int R, C; stage_rc(tid * 16 + i * 8192, R, C); const int Rb = Epi::PERM ? ((R & ~31) + perm32(R & 31)) : R;
;         voffA[i] = (unsigned)(R * K + C) * 2u; voffB[i] = (unsigned)(Rb * K + C) * 2u; }
;     const size_t kstep = (size_t)(BK * 2);
;     const size_t hstep = (size_t)HALF * K * 2;
;     const size_t tstep = 2 * hstep;
;     const unsigned ldsw = (unsigned)wid * 1024u;
;     const int aoff = lds_byte(wr * 64 + fr, fq * 8), boff = lds_byte(wc * 32 + fr, fq * 8);
;     ...
;     Unit cur, nxt; int ui = 0;
;     if (!S.next(0, cur)) return;
;     f32x4 acc[2][2][4][2];
; #pragma unroll
;     for (int a = 0; a < 2; ++a)
; #pragma unroll
;         for (int b = 0; b < 2; ++b)
; #pragma unroll
;             for (int m = 0; m < 4; ++m)
; #pragma unroll
;                 for (int n = 0; n < 2; ++n) acc[a][b][m][n] = (f32x4){0.f, 0.f, 0.f, 0.f};
;     bf16x8 At[4][2], B0[2][2], B1[2][2];
;     const char* cA = (const char*)g.A + (size_t)cur.pm * tstep; const char* cB = (const char*)g.Bt + (size_t)cur.pn * tstep;
;     S.a_ready(cur);
;     if constexpr (SP2) {
;         PG8_STAGE(PG8_SB(0, 0), cB, voffB); PG8_STAGE(PG8_SB(0, 1), cB + hstep, voffB); PG8_STAGE(PG8_SA(0, 0), cA, voffA); PG8_STAGE(PG8_SA(0, 1), cA + hstep, voffA);
;         if (wr == 1) PG8_BAR;
;         PG8_WAIT_V(2); PG8_BAR;
;         PG8_STAGE(PG8_SB(1, 0), cB + kstep, voffB); PG8_STAGE(PG8_SA(1, 0), cA + kstep, voffA); PG8_STAGE(PG8_SB(1, 1), cB + hstep + kstep, voffB);
;         PG8_WAIT_V(6); PG8_BAR;
.LBB0_704:
	s_cmp_lt_i32 s30, 8
	s_cselect_b64 s[4:5], -1, 0
	s_and_b64 s[4:5], s[4:5], s[0:1]
	s_andn2_b64 vcc, exec, s[4:5]
	s_cbranch_vccnz .LBB0_721
	s_cmpk_gt_i32 s2, 0x15ff
	v_readfirstlane_b32 s1, v152
	s_cbranch_scc1 .LBB0_721
	v_lshrrev_b32_e32 v2, 1, v152
	v_and_b32_e32 v11, 24, v2
	v_lshrrev_b32_e32 v2, 5, v152
	v_and_b32_e32 v2, 4, v2
	v_bfe_u32 v3, v152, 2, 2
	v_lshlrev_b32_e32 v0, 4, v152
	v_and_b32_e32 v1, 32, v152
	v_bfe_u32 v10, v152, 2, 4
	v_or3_b32 v2, v2, v3, v11
	v_lshrrev_b32_e32 v3, 3, v152
	s_movk_i32 s0, 0x70
	v_bitop3_b32 v8, v0, v1, 48 bitop3:0x6c
	v_and_b32_e32 v9, 64, v152
	v_and_or_b32 v4, v3, s0, v10
	s_movk_i32 s0, 0x60
	v_add_u32_e32 v12, 0x2000, v0
	s_add_u32 s46, s28, 0xb00000
	v_or_b32_e32 v1, v8, v9
	v_and_or_b32 v3, v3, s0, v2
	v_lshrrev_b32_e32 v0, 7, v12
	s_movk_i32 s0, 0xf0
	s_addc_u32 s47, s29, 0
	v_lshl_or_b32 v130, v3, 11, v1
	v_and_or_b32 v3, v0, s0, v10
	s_movk_i32 s0, 0xe0
	s_ashr_i32 s53, s2, 31
	v_and_or_b32 v0, v0, s0, v2
	s_lshr_b32 s0, s53, 29
	s_add_i32 s0, s2, s0
	s_lshr_b32 s10, s1, 6
	s_ashr_i32 s6, s0, 3
	s_and_b32 s0, s0, -8
	s_lshr_b32 s12, s1, 8
	s_lshl_b32 s52, s10, 10
	s_sub_i32 s0, s2, s0
	s_cmp_lt_i32 s0, 0
	s_movk_i32 s54, 0x2c1
	s_cselect_b32 s7, s54, 0x2c0
	s_mul_i32 s0, s0, s7
	s_add_i32 s0, s0, s6
	s_mul_hi_i32 s6, s0, 0x2e8ba2e9
	s_lshr_b32 s7, s6, 31
	s_ashr_i32 s6, s6, 5
	s_add_i32 s6, s6, s7
	s_lshl_b32 s7, s6, 3
	s_mulk_i32 s6, 0xb0
	s_sub_i32 s6, s0, s6
	s_sext_i32_i16 s0, s6
	s_bfe_u32 s0, s0, 0x3001c
	s_add_i32 s8, s6, s0
	s_sext_i32_i16 s0, s8
	s_and_b32 s8, s8, 0xfff8
	s_sub_i32 s6, s6, s8
	s_sext_i32_i16 s6, s6
	s_lshr_b32 s0, s0, 3
	s_add_i32 s38, s7, s6
	s_ashr_i32 s39, s38, 31
	s_bfe_i64 s[8:9], s[0:1], 0x100000
	s_lshl_b64 s[6:7], s[38:39], 19
	s_lshl_b64 s[8:9], s[8:9], 19
	s_add_u32 s42, s46, s8
	s_addc_u32 s43, s47, s9
	s_add_i32 s39, s52, 0
	s_add_i32 m0, s39, 0x10000
	v_lshl_or_b32 v134, v0, 11, v1
	global_load_lds_dwordx4 v130, s[42:43]
	s_add_i32 m0, s39, 0x12000
	s_add_u32 s8, s42, 0x40000
	global_load_lds_dwordx4 v134, s[42:43]
	s_addc_u32 s9, s43, 0
	s_add_i32 m0, s39, 0x14000
	v_lshl_or_b32 v128, v4, 11, v1
	global_load_lds_dwordx4 v130, s[8:9]
	s_add_i32 m0, s39, 0x16000
	s_add_u32 s40, s16, s6
	s_addc_u32 s41, s17, s7
	s_add_i32 s55, s39, 0x2000
	global_load_lds_dwordx4 v134, s[8:9]
	s_mov_b32 m0, s39
	s_add_u32 s6, s40, 0x40000
	v_lshl_or_b32 v132, v3, 11, v1
	global_load_lds_dwordx4 v128, s[40:41]
	s_mov_b32 m0, s55
	s_addc_u32 s7, s41, 0
	s_add_i32 s56, s39, 0x4000
	global_load_lds_dwordx4 v132, s[40:41]
	s_mov_b32 m0, s56
	s_add_i32 s57, s39, 0x6000
	global_load_lds_dwordx4 v128, s[6:7]
	s_mov_b32 m0, s57
	v_mov_b32_e32 v131, 0
	global_load_lds_dwordx4 v132, s[6:7]
	v_mov_b32_e32 v135, v131
	v_mov_b32_e32 v129, v131
	v_mov_b32_e32 v133, v131
	s_cmp_eq_u32 s12, 1
	s_mov_b32 s58, 0
	v_lshl_add_u64 v[6:7], s[42:43], 0, v[130:131]
	v_lshl_add_u64 v[4:5], s[42:43], 0, v[134:135]
	v_lshl_add_u64 v[0:1], s[40:41], 0, v[128:129]
	s_cselect_b64 s[6:7], -1, 0
	s_cmp_lg_u32 s12, 1
	v_lshl_add_u64 v[2:3], s[40:41], 0, v[132:133]
	s_add_u32 s8, s28, 0xfa00000
	s_addc_u32 s9, s29, 0
	s_lshl_b32 s10, s10, 5
	s_and_b32 s22, s10, 0x60
	s_mov_b64 s[10:11], 0x80
	s_add_i32 m0, s39, 0x18000
	v_lshl_add_u64 v[6:7], v[6:7], 0, s[10:11]
	s_ashr_i32 s59, s3, 31
	s_lshl_b32 s13, s12, 13
	s_lshl_b32 s23, s22, 7
	global_load_lds_dwordx4 v[6:7], off
	v_lshl_add_u64 v[4:5], v[4:5], 0, s[10:11]
	s_add_i32 m0, s39, 0x1a000
	s_add_i32 s60, s39, 0x8000
	s_add_i32 s61, s39, 0xa000
	global_load_lds_dwordx4 v[4:5], off
	v_lshl_add_u64 v[0:1], v[0:1], 0, s[10:11]
	s_mov_b32 m0, s60
	s_add_u32 s20, s42, 0x40080
	global_load_lds_dwordx4 v[0:1], off
	v_lshl_add_u64 v[0:1], v[2:3], 0, s[10:11]
	s_mov_b32 m0, s61
	s_addc_u32 s21, s43, 0
	global_load_lds_dwordx4 v[0:1], off
	s_add_i32 m0, s39, 0x1c000
	v_lshl_add_u64 v[0:1], s[20:21], 0, v[130:131]
	global_load_lds_dwordx4 v[0:1], off
	v_lshl_add_u64 v[0:1], s[20:21], 0, v[134:135]
	s_add_i32 m0, s39, 0x1e000
	s_sext_i32_i16 s71, s0
	global_load_lds_dwordx4 v[0:1], off
	s_cmp_lg_u32 s12, 1
	s_cbranch_scc1 .LBB0_708
	s_barrier
.LBB0_708:
	s_waitcnt vmcnt(8)
	s_barrier
	v_and_b32_e32 v0, 15, v152
	v_lshlrev_b32_e32 v1, 1, v11
	v_lshlrev_b32_e32 v2, 6, v152
	s_movk_i32 s0, 0x3c0
	v_lshlrev_b32_e32 v3, 2, v152
	v_and_or_b32 v2, v2, s0, v1
	v_and_b32_e32 v3, 32, v3
	v_lshl_or_b32 v144, s12, 6, v0
	v_lshl_or_b32 v0, v0, 6, v1
	v_lshlrev_b32_e32 v1, 8, v152
	v_bitop3_b32 v145, s23, v2, v3 bitop3:0xf6
	v_and_b32_e32 v1, 0x38000, v1
	v_lshlrev_b32_e32 v2, 11, v10
	v_or3_b32 v1, v8, v1, v2
	s_waitcnt vmcnt(0)
	v_add_u32_e32 v136, v1, v9
	v_lshlrev_b32_e32 v1, 4, v12
	s_waitcnt vmcnt(6)
	s_cmpk_lt_u32 s1, 0x100
	v_and_b32_e32 v1, 0x78000, v1
	v_bitop3_b32 v0, v0, s13, v3 bitop3:0xde
	s_cselect_b64 s[12:13], -1, 0
	v_or3_b32 v1, v8, v1, v2
	s_add_i32 s62, 0, 0x10000
	s_add_i32 s63, 0, 0x14000
	v_or_b32_e32 v146, s22, v11
	v_mov_b32_e32 v137, v131
	v_add_u32_e32 v138, v1, v9
	v_mov_b32_e32 v139, v131
	v_mov_b64_e32 v[140:141], 0x1600
	v_mov_b64_e32 v[142:143], 0x15ff
	v_add_u32_e32 v147, s62, v145
	v_add_u32_e32 v148, s63, v145
	v_add_u32_e32 v149, 0, v0
	s_movk_i32 s70, 0x1600
	s_barrier
	s_mov_b32 s77, 0
	s_branch .LBB0_711

;     __host__ __device__ bool next(int i, Unit& u) const {
;         const long L = (long)i * G + c; if (L >= nwg) return false;
;         int wgid = (int)L; { const int q = nwg / NXCD, r = nwg % NXCD, xcd = wgid % NXCD, off = wgid / NXCD; wgid = (xcd < r ? xcd * (q + 1) : r * (q + 1) + (xcd - r) * q) + off; }
;         const int nig = WGM * nN, gid = wgid / nig, fm = gid * WGM, gsz = (nM - fm) < WGM ? (nM - fm) : WGM;
; template <class Epi, class Sched, bool ALIGN_EPI = false, bool SP2 = false>
; __device__ __forceinline__ void gemm_phase(PG8_LAS unsigned char* lds, const Gemm g, const Sched& S, const Epi& E) {
;     const int tid = threadIdx.x, wid = __builtin_amdgcn_readfirstlane(tid >> 6), lane = tid & 63, wr = wid >> 2, wc = wid & 3, fr = lane & 15, fq = lane >> 4;
;     const int K = g.K, nt = K / BK;
;     unsigned voffA[2], voffB[2];
; #pragma unroll
;     for (int i = 0; i < 2; ++i) { int R, C; stage_rc(tid * 16 + i * 8192, R, C); const int Rb = Epi::PERM ? ((R & ~31) + perm32(R & 31)) : R;
;         voffA[i] = (unsigned)(R * K + C) * 2u; voffB[i] = (unsigned)(Rb * K + C) * 2u; }
;     const size_t kstep = (size_t)(BK * 2);
;     const size_t hstep = (size_t)HALF * K * 2;
;     const size_t tstep = 2 * hstep;
;     const unsigned ldsw = (unsigned)wid * 1024u;
;     const int aoff = lds_byte(wr * 64 + fr, fq * 8), boff = lds_byte(wc * 32 + fr, fq * 8);
;     ...
;     Unit cur, nxt; int ui = 0;
;     if (!S.next(0, cur)) return;
;     f32x4 acc[2][2][4][2];
; #pragma unroll
;     for (int a = 0; a < 2; ++a)
; #pragma unroll
;         for (int b = 0; b < 2; ++b)
; #pragma unroll
;             for (int m = 0; m < 4; ++m)
; #pragma unroll
;                 for (int n = 0; n < 2; ++n) acc[a][b][m][n] = (f32x4){0.f, 0.f, 0.f, 0.f};
;     bf16x8 At[4][2], B0[2][2], B1[2][2];
;     const char* cA = (const char*)g.A + (size_t)cur.pm * tstep; const char* cB = (const char*)g.Bt + (size_t)cur.pn * tstep;
;     S.a_ready(cur);
;     if constexpr (SP2) {
;         PG8_STAGE(PG8_SB(0, 0), cB, voffB); PG8_STAGE(PG8_SB(0, 1), cB + hstep, voffB); PG8_STAGE(PG8_SA(0, 0), cA, voffA); PG8_STAGE(PG8_SA(0, 1), cA + hstep, voffA);
;         if (wr == 1) PG8_BAR;
;         PG8_WAIT_V(2); PG8_BAR;
;         PG8_STAGE(PG8_SB(1, 0), cB + kstep, voffB); PG8_STAGE(PG8_SA(1, 0), cA + kstep, voffA); PG8_STAGE(PG8_SB(1, 1), cB + hstep + kstep, voffB);
;         PG8_WAIT_V(6); PG8_BAR;
.LBB0_771:
	s_cmp_lt_i32 s30, 9
	s_cselect_b64 s[4:5], -1, 0
	s_and_b64 s[6:7], s[4:5], s[0:1]
	s_andn2_b64 vcc, exec, s[6:7]
	s_cbranch_vccnz .LBB0_796
	s_cmpk_gt_i32 s2, 0x3ff
	v_readfirstlane_b32 s0, v152
	s_cbranch_scc1 .LBB0_796
	s_add_u32 s52, s28, 0xfa00000
	s_addc_u32 s53, s29, 0
	v_lshrrev_b32_e32 v3, 1, v152
	s_add_u32 s54, s28, 0x2100000
	v_and_b32_e32 v10, 24, v3
	v_lshrrev_b32_e32 v3, 5, v152
	s_addc_u32 s55, s29, 0
	v_and_b32_e32 v3, 4, v3
	v_bfe_u32 v4, v152, 2, 2
	s_ashr_i32 s57, s2, 31
	v_lshlrev_b32_e32 v0, 4, v152
	v_and_b32_e32 v1, 32, v152
	v_bfe_u32 v2, v152, 2, 4
	v_or3_b32 v3, v3, v4, v10
	v_lshrrev_b32_e32 v4, 3, v152
	s_movk_i32 s1, 0x70
	s_lshr_b32 s4, s57, 29
	v_bitop3_b32 v8, v0, v1, 48 bitop3:0x6c
	v_and_or_b32 v5, v4, s1, v2
	s_movk_i32 s1, 0x60
	v_add_u32_e32 v0, 0x2000, v0
	s_add_i32 s4, s2, s4
	v_and_or_b32 v4, v4, s1, v3
	v_lshrrev_b32_e32 v0, 7, v0
	s_movk_i32 s1, 0xf0
	s_and_b32 s8, s4, -8
	v_and_or_b32 v2, v0, s1, v2
	s_movk_i32 s1, 0xe0
	s_lshr_b32 s5, s0, 6
	s_sub_i32 s8, s2, s8
	v_and_or_b32 v0, v0, s1, v3
	s_lshr_b32 s1, s0, 8
	s_lshl_b32 s56, s5, 10
	s_lshl_b32 s10, s8, 7
	s_ashr_i32 s4, s4, 3
	s_mul_i32 s9, s8, 0x81
	s_cmp_lt_i32 s8, 0
	s_cselect_b32 s8, s9, s10
	s_add_i32 s4, s8, s4
	s_ashr_i32 s8, s4, 31
	s_lshr_b32 s8, s8, 27
	s_add_i32 s8, s4, s8
	s_ashr_i32 s9, s8, 5
	s_andn2_b32 s8, s8, 31
	s_sub_i32 s8, s4, s8
	s_bfe_i32 s4, s8, 0x80000
	s_bfe_u32 s4, s4, 0x3000c
	s_add_i32 s10, s8, s4
	s_bfe_i32 s4, s10, 0x80000
	s_and_b32 s10, s10, 0xf8
	s_sub_i32 s8, s8, s10
	s_lshl_b32 s9, s9, 3
	s_sext_i32_i16 s11, s4
	s_sext_i32_i8 s8, s8
	v_and_b32_e32 v9, 64, v152
	s_add_i32 s82, s9, s8
	s_ashr_i32 s8, s11, 3
	v_or_b32_e32 v1, v8, v9
	s_lshr_b32 s4, s11, 3
	s_mul_hi_i32 s9, s8, 0x160000
	s_mul_i32 s8, s8, 0x160000
	v_lshrrev_b32_e32 v1, 1, v1
	v_mul_u32_u24_e32 v4, 0xb00, v4
	s_add_u32 s44, s54, s8
	v_or_b32_e32 v4, v4, v1
	s_addc_u32 s45, s55, s9
	s_add_i32 s58, s56, 0
	v_lshlrev_b32_e32 v156, 1, v4
	v_mul_u32_u24_e32 v0, 0xb00, v0
	s_add_i32 m0, s58, 0x10000
	v_or_b32_e32 v0, v0, v1
	global_load_lds_dwordx4 v156, s[44:45]
	s_add_i32 m0, s58, 0x12000
	v_lshlrev_b32_e32 v160, 1, v0
	s_add_u32 s8, s44, 0xb0000
	global_load_lds_dwordx4 v160, s[44:45]
	s_addc_u32 s9, s45, 0
	s_add_i32 m0, s58, 0x14000
	s_mul_i32 s12, s82, 0x160000
	global_load_lds_dwordx4 v156, s[8:9]
	s_add_i32 m0, s58, 0x16000
	v_mul_u32_u24_e32 v11, 0xb00, v5
	s_mul_hi_i32 s10, s82, 0x160000
	s_add_u32 s42, s52, s12
	v_or_b32_e32 v5, v1, v11
	v_mul_u32_u24_e32 v12, 0xb00, v2
	s_addc_u32 s43, s53, s10
	s_add_i32 s59, s58, 0x2000
	v_lshlrev_b32_e32 v154, 1, v5
	v_or_b32_e32 v2, v12, v1
	global_load_lds_dwordx4 v160, s[8:9]
	s_mov_b32 m0, s58
	s_add_u32 s8, s42, 0xb0000
	v_lshlrev_b32_e32 v158, 1, v2
	global_load_lds_dwordx4 v154, s[42:43]
	s_mov_b32 m0, s59
	s_addc_u32 s9, s43, 0
	s_add_i32 s60, s58, 0x4000
	global_load_lds_dwordx4 v158, s[42:43]
	s_mov_b32 m0, s60
	s_add_i32 s61, s58, 0x6000
	global_load_lds_dwordx4 v154, s[8:9]
	s_mov_b32 m0, s61
	v_mov_b32_e32 v157, 0
	global_load_lds_dwordx4 v158, s[8:9]
	v_mov_b32_e32 v161, v157
	v_mov_b32_e32 v155, v157
	v_mov_b32_e32 v159, v157
	s_cmp_eq_u32 s1, 1
	s_mov_b32 s62, 0
	v_lshl_add_u64 v[6:7], s[44:45], 0, v[156:157]
	v_lshl_add_u64 v[4:5], s[44:45], 0, v[160:161]
	v_lshl_add_u64 v[0:1], s[42:43], 0, v[154:155]
	s_cselect_b64 s[8:9], -1, 0
	s_cmp_lg_u32 s1, 1
	v_lshl_add_u64 v[2:3], s[42:43], 0, v[158:159]
	s_add_u32 s10, s28, 0x2fa00000
	s_addc_u32 s11, s29, 0
	s_add_u32 s63, s28, 0x5000
	s_addc_u32 s70, s29, 0
	s_lshl_b32 s5, s5, 5
	s_mov_b64 s[12:13], 0x80
	s_and_b32 s5, s5, 0x60
	s_add_i32 m0, s58, 0x18000
	v_lshl_add_u64 v[6:7], v[6:7], 0, s[12:13]
	s_ashr_i32 s71, s3, 31
	s_lshl_b32 s22, s1, 13
	s_lshl_b32 s23, s5, 7
	global_load_lds_dwordx4 v[6:7], off
	v_lshl_add_u64 v[4:5], v[4:5], 0, s[12:13]
	s_add_i32 m0, s58, 0x1a000
	s_add_i32 s72, s58, 0x8000
	s_add_i32 s73, s58, 0xa000
	global_load_lds_dwordx4 v[4:5], off
	v_lshl_add_u64 v[0:1], v[0:1], 0, s[12:13]
	s_mov_b32 m0, s72
	s_add_u32 s20, s44, 0xb0080
	global_load_lds_dwordx4 v[0:1], off
	v_lshl_add_u64 v[0:1], v[2:3], 0, s[12:13]
	s_mov_b32 m0, s73
	s_addc_u32 s21, s45, 0
	global_load_lds_dwordx4 v[0:1], off
	s_add_i32 m0, s58, 0x1c000
	v_lshl_add_u64 v[0:1], s[20:21], 0, v[156:157]
	global_load_lds_dwordx4 v[0:1], off
	v_lshl_add_u64 v[0:1], s[20:21], 0, v[160:161]
	s_add_i32 m0, s58, 0x1e000
	s_sext_i32_i8 s83, s4
	global_load_lds_dwordx4 v[0:1], off
	s_cmp_lg_u32 s1, 1
	s_cbranch_scc1 .LBB0_775
	s_barrier
.LBB0_775:
	s_waitcnt vmcnt(8)
	s_barrier
	v_and_b32_e32 v0, 15, v152
	v_lshlrev_b32_e32 v1, 1, v10
	v_lshlrev_b32_e32 v2, 6, v152
	s_movk_i32 s4, 0x3c0
	v_lshlrev_b32_e32 v3, 2, v152
	v_and_or_b32 v2, v2, s4, v1
	v_and_b32_e32 v3, 32, v3
	v_lshl_or_b32 v200, s1, 6, v0
	v_lshl_or_b32 v0, v0, 6, v1
	s_waitcnt vmcnt(6)
	s_cmpk_lt_u32 s0, 0x100
	v_add_u16_e32 v1, v8, v9
	v_bitop3_b32 v0, v0, s22, v3 bitop3:0xde
	v_bitop3_b32 v201, s23, v2, v3 bitop3:0xf6
	s_cselect_b64 s[20:21], -1, 0
	v_lshrrev_b16_e32 v1, 1, v1
	s_add_i32 s74, 0, 0x10000
	s_add_i32 s75, 0, 0x14000
	v_or_b32_e32 v202, s5, v10
	v_add_lshl_u32 v162, v11, v1, 1
	v_mov_b32_e32 v163, v157
	v_add_lshl_u32 v164, v12, v1, 1
	v_mov_b32_e32 v165, v157
	v_mov_b64_e32 v[166:167], 0x400
	v_mov_b64_e32 v[168:169], 0x3ff
	v_add_u32_e32 v203, s74, v201
	v_add_u32_e32 v204, s75, v201
	v_add_u32_e32 v205, 0, v0
	s_mov_b64 s[22:23], 0x40000
	s_mov_b32 s76, 0x40000
	s_mov_b64 s[24:25], 0x48000
	s_mov_b32 s77, 0x48000
	s_mov_b64 s[36:37], 0x50000
	s_mov_b32 s78, 0x50000
	s_mov_b64 s[38:39], 0x58000
	s_mov_b32 s79, 0x58000
	s_barrier
	s_branch .LBB0_778

;     __host__ __device__ bool next(int i, Unit& u) const {
;         const long L = (long)i * G + c; if (L >= nwg) return false;
;         int wgid = (int)L; { const int q = nwg / NXCD, r = nwg % NXCD, xcd = wgid % NXCD, off = wgid / NXCD; wgid = (xcd < r ? xcd * (q + 1) : r * (q + 1) + (xcd - r) * q) + off; }
;         const int nig = WGM * nN, gid = wgid / nig, fm = gid * WGM, gsz = (nM - fm) < WGM ? (nM - fm) : WGM;
; template <class Epi, class Sched, bool ALIGN_EPI = false, bool SP2 = false>
; __device__ __forceinline__ void gemm_phase(PG8_LAS unsigned char* lds, const Gemm g, const Sched& S, const Epi& E) {
;     const int tid = threadIdx.x, wid = __builtin_amdgcn_readfirstlane(tid >> 6), lane = tid & 63, wr = wid >> 2, wc = wid & 3, fr = lane & 15, fq = lane >> 4;
;     const int K = g.K, nt = K / BK;
;     unsigned voffA[2], voffB[2];
; #pragma unroll
;     for (int i = 0; i < 2; ++i) { int R, C; stage_rc(tid * 16 + i * 8192, R, C); const int Rb = Epi::PERM ? ((R & ~31) + perm32(R & 31)) : R;
;         voffA[i] = (unsigned)(R * K + C) * 2u; voffB[i] = (unsigned)(Rb * K + C) * 2u; }
;     const size_t kstep = (size_t)(BK * 2);
;     const size_t hstep = (size_t)HALF * K * 2;
;     const size_t tstep = 2 * hstep;
;     const unsigned ldsw = (unsigned)wid * 1024u;
;     const int aoff = lds_byte(wr * 64 + fr, fq * 8), boff = lds_byte(wc * 32 + fr, fq * 8);
;     ...
;     Unit cur, nxt; int ui = 0;
;     if (!S.next(0, cur)) return;
;     f32x4 acc[2][2][4][2];
; #pragma unroll
;     for (int a = 0; a < 2; ++a)
; #pragma unroll
;         for (int b = 0; b < 2; ++b)
; #pragma unroll
;             for (int m = 0; m < 4; ++m)
; #pragma unroll
;                 for (int n = 0; n < 2; ++n) acc[a][b][m][n] = (f32x4){0.f, 0.f, 0.f, 0.f};
;     bf16x8 At[4][2], B0[2][2], B1[2][2];
;     const char* cA = (const char*)g.A + (size_t)cur.pm * tstep; const char* cB = (const char*)g.Bt + (size_t)cur.pn * tstep;
;     S.a_ready(cur);
;     if constexpr (SP2) {
;         PG8_STAGE(PG8_SB(0, 0), cB, voffB); PG8_STAGE(PG8_SB(0, 1), cB + hstep, voffB); PG8_STAGE(PG8_SA(0, 0), cA, voffA); PG8_STAGE(PG8_SA(0, 1), cA + hstep, voffA);
;         if (wr == 1) PG8_BAR;
;         PG8_WAIT_V(2); PG8_BAR;
;         PG8_STAGE(PG8_SB(1, 0), cB + kstep, voffB); PG8_STAGE(PG8_SA(1, 0), cA + kstep, voffA); PG8_STAGE(PG8_SB(1, 1), cB + hstep + kstep, voffB);
;         PG8_WAIT_V(6); PG8_BAR;
.LBB0_906:
	s_andn2_b64 vcc, exec, s[0:1]
	s_cbranch_vccnz .LBB0_938
	v_lshrrev_b32_e32 v2, 1, v152
	v_and_b32_e32 v11, 24, v2
	v_lshrrev_b32_e32 v2, 5, v152
	v_and_b32_e32 v2, 4, v2
	v_bfe_u32 v3, v152, 2, 2
	v_lshlrev_b32_e32 v0, 4, v152
	v_and_b32_e32 v1, 32, v152
	v_bfe_u32 v10, v152, 2, 4
	v_or3_b32 v2, v2, v3, v11
	v_lshrrev_b32_e32 v3, 3, v152
	s_movk_i32 s0, 0x70
	v_bitop3_b32 v8, v0, v1, 48 bitop3:0x6c
	v_and_b32_e32 v9, 64, v152
	v_and_or_b32 v4, v3, s0, v10
	s_movk_i32 s0, 0x60
	v_add_u32_e32 v12, 0x2000, v0
	s_add_u32 s60, s28, 0x2d00000
	v_or_b32_e32 v1, v8, v9
	v_and_or_b32 v3, v3, s0, v2
	v_lshrrev_b32_e32 v0, 7, v12
	s_movk_i32 s0, 0xf0
	s_addc_u32 s61, s29, 0
	v_lshl_or_b32 v130, v3, 11, v1
	v_and_or_b32 v3, v0, s0, v10
	s_movk_i32 s0, 0xe0
	s_lshr_b32 s1, s22, 6
	s_ashr_i32 s5, s4, 31
	s_ashr_i32 s53, s52, 31
	v_and_or_b32 v0, v0, s0, v2
	s_lshr_b32 s0, s22, 8
	s_lshl_b32 s62, s1, 10
	s_lshl_b64 s[8:9], s[4:5], 19
	s_lshl_b64 s[10:11], s[52:53], 19
	s_add_u32 s56, s16, s10
	s_addc_u32 s57, s17, s11
	s_add_i32 s53, s62, 0
	s_add_i32 m0, s53, 0x10000
	v_lshl_or_b32 v134, v0, 11, v1
	global_load_lds_dwordx4 v130, s[56:57]
	s_add_i32 m0, s53, 0x12000
	s_add_u32 s10, s56, 0x40000
	global_load_lds_dwordx4 v134, s[56:57]
	s_addc_u32 s11, s57, 0
	s_add_i32 m0, s53, 0x14000
	v_lshl_or_b32 v128, v4, 11, v1
	global_load_lds_dwordx4 v130, s[10:11]
	s_add_i32 m0, s53, 0x16000
	s_add_u32 s54, s60, s8
	s_addc_u32 s55, s61, s9
	s_add_i32 s63, s53, 0x2000
	global_load_lds_dwordx4 v134, s[10:11]
	s_mov_b32 m0, s53
	s_add_u32 s8, s54, 0x40000
	v_lshl_or_b32 v132, v3, 11, v1
	global_load_lds_dwordx4 v128, s[54:55]
	s_mov_b32 m0, s63
	s_addc_u32 s9, s55, 0
	s_add_i32 s70, s53, 0x4000
	global_load_lds_dwordx4 v132, s[54:55]
	s_mov_b32 m0, s70
	s_add_i32 s71, s53, 0x6000
	global_load_lds_dwordx4 v128, s[8:9]
	s_mov_b32 m0, s71
	v_mov_b32_e32 v131, 0
	global_load_lds_dwordx4 v132, s[8:9]
	v_mov_b32_e32 v135, v131
	v_mov_b32_e32 v129, v131
	v_mov_b32_e32 v133, v131
	s_cmp_eq_u32 s0, 1
	s_mov_b64 s[96:97], s[66:67]
	s_mov_b32 s72, 0
	v_lshl_add_u64 v[6:7], s[56:57], 0, v[130:131]
	v_lshl_add_u64 v[4:5], s[56:57], 0, v[134:135]
	v_lshl_add_u64 v[0:1], s[54:55], 0, v[128:129]
	s_cselect_b64 s[8:9], -1, 0
	s_cmp_lg_u32 s0, 1
	v_lshl_add_u64 v[2:3], s[54:55], 0, v[132:133]
	s_add_u32 s10, s28, 0xfa00000
	v_readlane_b32 s76, v255, 4
	s_addc_u32 s11, s29, 0
	s_ashr_i32 s73, s3, 31
	s_ashr_i32 s74, s2, 31
	v_readlane_b32 s88, v255, 16
	v_readlane_b32 s89, v255, 17
	s_cmp_lg_u64 s[88:89], 0
	s_cselect_b64 s[12:13], -1, 0
	s_lshl_b32 s1, s1, 5
	s_mov_b64 s[20:21], 0x80
	s_and_b32 s1, s1, 0x60
	s_add_i32 m0, s53, 0x18000
	v_lshl_add_u64 v[6:7], v[6:7], 0, s[20:21]
	s_lshl_b32 s5, s0, 13
	s_lshl_b32 s23, s1, 7
	global_load_lds_dwordx4 v[6:7], off
	v_lshl_add_u64 v[4:5], v[4:5], 0, s[20:21]
	s_add_i32 m0, s53, 0x1a000
	s_add_i32 s75, s53, 0x8000
	s_add_i32 s76, s53, 0xa000
	global_load_lds_dwordx4 v[4:5], off
	v_lshl_add_u64 v[0:1], v[0:1], 0, s[20:21]
	s_mov_b32 m0, s75
	s_add_u32 s24, s56, 0x40080
	global_load_lds_dwordx4 v[0:1], off
	v_lshl_add_u64 v[0:1], v[2:3], 0, s[20:21]
	s_mov_b32 m0, s76
	s_addc_u32 s25, s57, 0
	global_load_lds_dwordx4 v[0:1], off
	s_add_i32 m0, s53, 0x1c000
	v_lshl_add_u64 v[0:1], s[24:25], 0, v[130:131]
	global_load_lds_dwordx4 v[0:1], off
	v_lshl_add_u64 v[0:1], s[24:25], 0, v[134:135]
	s_add_i32 m0, s53, 0x1e000
	v_lshlrev_b32_e32 v2, 6, v152
	global_load_lds_dwordx4 v[0:1], off
	s_cmp_lg_u32 s0, 1
	s_cbranch_scc1 .LBB0_909
	s_barrier
.LBB0_909:
	s_waitcnt vmcnt(8)
	s_barrier
	v_and_b32_e32 v0, 15, v152
	v_lshlrev_b32_e32 v1, 1, v11
	s_movk_i32 s24, 0x3c0
	v_lshlrev_b32_e32 v3, 2, v152
	v_and_or_b32 v2, v2, s24, v1
	v_and_b32_e32 v3, 32, v3
	v_lshl_or_b32 v155, s0, 6, v0
	v_lshl_or_b32 v0, v0, 6, v1
	v_lshlrev_b32_e32 v1, 8, v152
	v_bitop3_b32 v157, s23, v2, v3 bitop3:0xf6
	v_and_b32_e32 v1, 0x38000, v1
	v_lshlrev_b32_e32 v2, 11, v10
	v_or3_b32 v1, v8, v1, v2
	s_waitcnt vmcnt(0)
	v_add_u32_e32 v136, v1, v9
	v_lshlrev_b32_e32 v1, 4, v12
	v_readlane_b32 s78, v255, 6
	v_readlane_b32 s79, v255, 7
	s_waitcnt vmcnt(6)
	s_cmpk_lt_u32 s22, 0x100
	v_and_b32_e32 v1, 0x78000, v1
	v_readlane_b32 s77, v255, 5
	v_bitop3_b32 v0, v0, s5, v3 bitop3:0xde
	s_cselect_b64 s[22:23], -1, 0
	v_or3_b32 v1, v8, v1, v2
	s_add_i32 s78, 0, 0x10000
	s_add_i32 s79, 0, 0x14000
	v_or_b32_e32 v158, s1, v11
	v_mov_b32_e32 v137, v131
	v_add_u32_e32 v138, v1, v9
	v_mov_b32_e32 v139, v131
	v_mov_b64_e32 v[140:141], 0xc00
	v_mov_b64_e32 v[142:143], 0xbff
	s_movk_i32 s77, 0x181
	v_add_u32_e32 v159, s78, v157
	v_add_u32_e32 v160, s79, v157
	v_add_u32_e32 v161, 0, v0
	s_mov_b64 s[24:25], 0x1000000
	s_mov_b32 s64, 0x1000000
	s_mov_b64 s[36:37], 0x1200000
	s_mov_b32 s65, 0x1200000
	s_mov_b64 s[38:39], 0x1400000
	s_mov_b32 s66, 0x1400000
	s_mov_b64 s[40:41], 0x1600000
	s_mov_b32 s67, 0x1600000
	v_readlane_b32 s80, v255, 8
	v_readlane_b32 s81, v255, 9
	v_readlane_b32 s82, v255, 10
	v_readlane_b32 s83, v255, 11
	v_readlane_b32 s84, v255, 12
	v_readlane_b32 s85, v255, 13
	v_readlane_b32 s86, v255, 14
	v_readlane_b32 s87, v255, 15
	v_readlane_b32 s90, v255, 18
	v_readlane_b32 s91, v255, 19
	v_readlane_b32 s92, v255, 16
	v_readlane_b32 s93, v255, 17
	s_nop 2
	v_lshl_add_u32 v240, s4, 8, v155
	v_ashrrev_i32_e32 v241, 31, v240
	v_lshl_add_u64 v[238:239], v[240:241], 2, s[92:93]
	global_load_dword v230, v[238:239], off
	global_load_dword v231, v[238:239], off offset:64
	global_load_dword v232, v[238:239], off offset:128
	global_load_dword v233, v[238:239], off offset:192
	global_load_dword v234, v[238:239], off offset:512
	global_load_dword v235, v[238:239], off offset:576
	global_load_dword v236, v[238:239], off offset:640
	global_load_dword v237, v[238:239], off offset:704
	s_barrier
	s_mov_b32 s32, 0
	s_branch .LBB0_912

;     __host__ __device__ bool next(int i, Unit& u) const {
;         const long L = (long)i * G + c; if (L >= nwg) return false;
;         int wgid = (int)L; { const int q = nwg / NXCD, r = nwg % NXCD, xcd = wgid % NXCD, off = wgid / NXCD; wgid = (xcd < r ? xcd * (q + 1) : r * (q + 1) + (xcd - r) * q) + off; }
;         const int nig = WGM * nN, gid = wgid / nig, fm = gid * WGM, gsz = (nM - fm) < WGM ? (nM - fm) : WGM;
; template <class Epi, class Sched, bool ALIGN_EPI = false, bool SP2 = false>
; __device__ __forceinline__ void gemm_phase(PG8_LAS unsigned char* lds, const Gemm g, const Sched& S, const Epi& E) {
;     const int tid = threadIdx.x, wid = __builtin_amdgcn_readfirstlane(tid >> 6), lane = tid & 63, wr = wid >> 2, wc = wid & 3, fr = lane & 15, fq = lane >> 4;
;     const int K = g.K, nt = K / BK;
;     unsigned voffA[2], voffB[2];
; #pragma unroll
;     for (int i = 0; i < 2; ++i) { int R, C; stage_rc(tid * 16 + i * 8192, R, C); const int Rb = Epi::PERM ? ((R & ~31) + perm32(R & 31)) : R;
;         voffA[i] = (unsigned)(R * K + C) * 2u; voffB[i] = (unsigned)(Rb * K + C) * 2u; }
;     const size_t kstep = (size_t)(BK * 2);
;     const size_t hstep = (size_t)HALF * K * 2;
;     const size_t tstep = 2 * hstep;
;     const unsigned ldsw = (unsigned)wid * 1024u;
;     const int aoff = lds_byte(wr * 64 + fr, fq * 8), boff = lds_byte(wc * 32 + fr, fq * 8);
;     ...
;     Unit cur, nxt; int ui = 0;
;     if (!S.next(0, cur)) return;
;     f32x4 acc[2][2][4][2];
; #pragma unroll
;     for (int a = 0; a < 2; ++a)
; #pragma unroll
;         for (int b = 0; b < 2; ++b)
; #pragma unroll
;             for (int m = 0; m < 4; ++m)
; #pragma unroll
;                 for (int n = 0; n < 2; ++n) acc[a][b][m][n] = (f32x4){0.f, 0.f, 0.f, 0.f};
;     bf16x8 At[4][2], B0[2][2], B1[2][2];
;     const char* cA = (const char*)g.A + (size_t)cur.pm * tstep; const char* cB = (const char*)g.Bt + (size_t)cur.pn * tstep;
;     S.a_ready(cur);
;     if constexpr (SP2) {
;         PG8_STAGE(PG8_SB(0, 0), cB, voffB); PG8_STAGE(PG8_SB(0, 1), cB + hstep, voffB); PG8_STAGE(PG8_SA(0, 0), cA, voffA); PG8_STAGE(PG8_SA(0, 1), cA + hstep, voffA);
;         if (wr == 1) PG8_BAR;
;         PG8_WAIT_V(2); PG8_BAR;
;         PG8_STAGE(PG8_SB(1, 0), cB + kstep, voffB); PG8_STAGE(PG8_SA(1, 0), cA + kstep, voffA); PG8_STAGE(PG8_SB(1, 1), cB + hstep + kstep, voffB);
;         PG8_WAIT_V(6); PG8_BAR;
.LBB0_1196:
	s_cmp_lt_i32 s30, 14
	s_cselect_b64 s[4:5], -1, 0
	s_and_b64 s[6:7], s[4:5], s[0:1]
	s_andn2_b64 vcc, exec, s[6:7]
	s_cbranch_vccnz .LBB0_1225
	s_cmpk_gt_i32 s2, 0x3ff
	v_readfirstlane_b32 s1, v152
	s_cbranch_scc1 .LBB0_1225
	s_waitcnt vmcnt(0)
	v_lshrrev_b32_e32 v2, 1, v152
	v_and_b32_e32 v11, 24, v2
	v_lshrrev_b32_e32 v2, 5, v152
	v_and_b32_e32 v2, 4, v2
	v_bfe_u32 v3, v152, 2, 2
	v_lshlrev_b32_e32 v0, 4, v152
	v_and_b32_e32 v1, 32, v152
	v_bfe_u32 v10, v152, 2, 4
	v_or3_b32 v2, v2, v3, v11
	v_lshrrev_b32_e32 v3, 3, v152
	s_movk_i32 s0, 0x70
	v_bitop3_b32 v8, v0, v1, 48 bitop3:0x6c
	v_and_b32_e32 v9, 64, v152
	v_and_or_b32 v4, v3, s0, v10
	s_movk_i32 s0, 0x60
	v_add_u32_e32 v12, 0x2000, v0
	s_add_u32 s56, s28, 0x3300000
	v_or_b32_e32 v1, v8, v9
	v_and_or_b32 v3, v3, s0, v2
	v_lshrrev_b32_e32 v0, 7, v12
	s_movk_i32 s0, 0xf0
	s_addc_u32 s57, s29, 0
	v_lshl_or_b32 v150, v3, 11, v1
	v_and_or_b32 v3, v0, s0, v10
	s_movk_i32 s0, 0xe0
	s_ashr_i32 s59, s2, 31
	v_and_or_b32 v0, v0, s0, v2
	s_lshr_b32 s0, s59, 29
	s_add_i32 s0, s2, s0
	s_and_b32 s4, s0, -8
	s_lshr_b32 s20, s1, 6
	s_sub_i32 s4, s2, s4
	s_lshr_b32 s22, s1, 8
	s_lshl_b32 s58, s20, 10
	s_lshl_b32 s8, s4, 7
	s_ashr_i32 s0, s0, 3
	s_mul_i32 s5, s4, 0x81
	s_cmp_lt_i32 s4, 0
	s_cselect_b32 s4, s5, s8
	s_add_i32 s0, s4, s0
	s_ashr_i32 s4, s0, 31
	s_lshr_b32 s4, s4, 27
	s_add_i32 s4, s0, s4
	s_ashr_i32 s5, s4, 5
	s_andn2_b32 s4, s4, 31
	s_sub_i32 s4, s0, s4
	s_bfe_i32 s0, s4, 0x80000
	s_bfe_u32 s0, s0, 0x3000c
	s_add_i32 s8, s4, s0
	s_bfe_i32 s0, s8, 0x80000
	s_and_b32 s8, s8, 0xf8
	s_sub_i32 s4, s4, s8
	s_lshl_b32 s5, s5, 3
	s_sext_i32_i16 s0, s0
	s_sext_i32_i8 s4, s4
	s_lshr_b32 s0, s0, 3
	s_add_i32 s48, s5, s4
	s_ashr_i32 s49, s48, 31
	s_bfe_i64 s[8:9], s[0:1], 0x100000
	s_lshl_b64 s[4:5], s[48:49], 19
	s_lshl_b64 s[8:9], s[8:9], 19
	s_add_u32 s52, s56, s8
	s_addc_u32 s53, s57, s9
	s_add_i32 s49, s58, 0
	s_add_i32 m0, s49, 0x10000
	v_lshl_or_b32 v156, v0, 11, v1
	global_load_lds_dwordx4 v150, s[52:53]
	s_add_i32 m0, s49, 0x12000
	s_add_u32 s8, s52, 0x40000
	global_load_lds_dwordx4 v156, s[52:53]
	s_addc_u32 s9, s53, 0
	s_add_i32 m0, s49, 0x14000
	v_lshl_or_b32 v148, v4, 11, v1
	global_load_lds_dwordx4 v150, s[8:9]
	s_add_i32 m0, s49, 0x16000
	s_add_u32 s4, s16, s4
	s_addc_u32 s5, s17, s5
	s_add_i32 s60, s49, 0x2000
	global_load_lds_dwordx4 v156, s[8:9]
	s_mov_b32 m0, s49
	s_add_u32 s8, s4, 0x40000
	v_lshl_or_b32 v154, v3, 11, v1
	global_load_lds_dwordx4 v148, s[4:5]
	s_mov_b32 m0, s60
	s_addc_u32 s9, s5, 0
	s_add_i32 s61, s49, 0x4000
	global_load_lds_dwordx4 v154, s[4:5]
	s_mov_b32 m0, s61
	s_add_i32 s62, s49, 0x6000
	global_load_lds_dwordx4 v148, s[8:9]
	s_mov_b32 m0, s62
	v_mov_b32_e32 v151, 0
	global_load_lds_dwordx4 v154, s[8:9]
	v_mov_b32_e32 v157, v151
	v_mov_b32_e32 v149, v151
	v_mov_b32_e32 v155, v151
	s_cmp_eq_u32 s22, 1
	s_mov_b64 s[84:85], s[66:67]
	s_mov_b32 s63, 0
	v_lshl_add_u64 v[6:7], s[52:53], 0, v[150:151]
	v_lshl_add_u64 v[4:5], s[52:53], 0, v[156:157]
	s_mov_b64 s[8:9], 0x40000
	v_lshl_add_u64 v[0:1], s[4:5], 0, v[148:149]
	s_cselect_b64 s[10:11], -1, 0
	s_cmp_lg_u32 s22, 1
	v_lshl_add_u64 v[2:3], s[4:5], 0, v[154:155]
	s_add_u32 s12, s28, 0x2fa00000
	s_addc_u32 s13, s29, 0
	s_add_u32 s64, s28, 0x38000
	s_addc_u32 s65, s29, 0
	s_ashr_i32 s66, s3, 31
	s_cmp_lg_u64 s[18:19], 0
	s_cselect_b64 s[14:15], -1, 0
	s_lshl_b32 s20, s20, 5
	s_and_b32 s33, s20, 0x60
	s_mov_b64 s[20:21], 0x80
	s_add_i32 m0, s49, 0x18000
	v_lshl_add_u64 v[6:7], v[6:7], 0, s[20:21]
	s_lshl_b32 s23, s22, 13
	s_lshl_b32 s34, s33, 7
	global_load_lds_dwordx4 v[6:7], off
	v_lshl_add_u64 v[4:5], v[4:5], 0, s[20:21]
	s_add_i32 m0, s49, 0x1a000
	s_add_i32 s67, s49, 0x8000
	s_add_i32 s68, s49, 0xa000
	global_load_lds_dwordx4 v[4:5], off
	v_lshl_add_u64 v[0:1], v[0:1], 0, s[20:21]
	s_mov_b32 m0, s67
	s_add_u32 s24, s52, 0x40080
	global_load_lds_dwordx4 v[0:1], off
	v_lshl_add_u64 v[0:1], v[2:3], 0, s[20:21]
	s_mov_b32 m0, s68
	s_addc_u32 s25, s53, 0
	global_load_lds_dwordx4 v[0:1], off
	s_add_i32 m0, s49, 0x1c000
	v_lshl_add_u64 v[0:1], s[24:25], 0, v[150:151]
	global_load_lds_dwordx4 v[0:1], off
	v_lshl_add_u64 v[0:1], s[24:25], 0, v[156:157]
	s_add_i32 m0, s49, 0x1e000
	s_sext_i32_i8 s75, s0
	global_load_lds_dwordx4 v[0:1], off
	s_cmp_lg_u32 s22, 1
	s_cbranch_scc1 .LBB0_1200
	s_barrier
.LBB0_1200:
	s_waitcnt vmcnt(8)
	s_barrier
	v_and_b32_e32 v0, 15, v152
	v_lshlrev_b32_e32 v1, 1, v11
	v_lshlrev_b32_e32 v2, 6, v152
	s_movk_i32 s0, 0x3c0
	v_lshlrev_b32_e32 v3, 2, v152
	v_and_or_b32 v2, v2, s0, v1
	v_and_b32_e32 v3, 32, v3
	v_lshl_or_b32 v178, s22, 6, v0
	v_lshl_or_b32 v0, v0, 6, v1
	v_lshlrev_b32_e32 v1, 8, v152
	v_bitop3_b32 v179, s34, v2, v3 bitop3:0xf6
	v_and_b32_e32 v1, 0x38000, v1
	v_lshlrev_b32_e32 v2, 11, v10
	v_or3_b32 v1, v8, v1, v2
	v_add_u32_e32 v158, v1, v9
	v_lshlrev_b32_e32 v1, 4, v12
	s_waitcnt vmcnt(6)
	s_cmpk_lt_u32 s1, 0x100
	v_and_b32_e32 v1, 0x78000, v1
	v_bitop3_b32 v0, v0, s23, v3 bitop3:0xde
	s_cselect_b64 s[22:23], -1, 0
	v_or3_b32 v1, v8, v1, v2
	s_add_i32 s69, 0, 0x10000
	s_add_i32 s70, 0, 0x14000
	v_or_b32_e32 v180, s33, v11
	v_mov_b32_e32 v159, v151
	v_add_u32_e32 v160, v1, v9
	v_mov_b32_e32 v161, v151
	v_mov_b64_e32 v[162:163], 0x400
	v_mov_b64_e32 v[164:165], 0x3ff
	v_add_u32_e32 v181, s69, v179
	v_add_u32_e32 v182, s70, v179
	v_add_u32_e32 v183, 0, v0
	s_mov_b32 s71, 0x40000
	s_mov_b64 s[24:25], 0x48000
	s_mov_b32 s72, 0x48000
	s_mov_b64 s[36:37], 0x50000
	s_mov_b32 s73, 0x50000
	s_mov_b64 s[38:39], 0x58000
	s_mov_b32 s74, 0x58000
	s_barrier
	s_branch .LBB0_1203

;     __host__ __device__ bool next(int i, Unit& u) const {
;         const long L = (long)i * G + c; if (L >= nwg) return false;
;         int wgid = (int)L; { const int q = nwg / NXCD, r = nwg % NXCD, xcd = wgid % NXCD, off = wgid / NXCD; wgid = (xcd < r ? xcd * (q + 1) : r * (q + 1) + (xcd - r) * q) + off; }
;         const int nig = WGM * nN, gid = wgid / nig, fm = gid * WGM, gsz = (nM - fm) < WGM ? (nM - fm) : WGM;
; template <class Epi, class Sched, bool ALIGN_EPI = false, bool SP2 = false>
; __device__ __forceinline__ void gemm_phase(PG8_LAS unsigned char* lds, const Gemm g, const Sched& S, const Epi& E) {
;     const int tid = threadIdx.x, wid = __builtin_amdgcn_readfirstlane(tid >> 6), lane = tid & 63, wr = wid >> 2, wc = wid & 3, fr = lane & 15, fq = lane >> 4;
;     const int K = g.K, nt = K / BK;
;     unsigned voffA[2], voffB[2];
; #pragma unroll
;     for (int i = 0; i < 2; ++i) { int R, C; stage_rc(tid * 16 + i * 8192, R, C); const int Rb = Epi::PERM ? ((R & ~31) + perm32(R & 31)) : R;
;         voffA[i] = (unsigned)(R * K + C) * 2u; voffB[i] = (unsigned)(Rb * K + C) * 2u; }
;     const size_t kstep = (size_t)(BK * 2);
;     const size_t hstep = (size_t)HALF * K * 2;
;     const size_t tstep = 2 * hstep;
;     const unsigned ldsw = (unsigned)wid * 1024u;
;     const int aoff = lds_byte(wr * 64 + fr, fq * 8), boff = lds_byte(wc * 32 + fr, fq * 8);
;     ...
;     Unit cur, nxt; int ui = 0;
;     if (!S.next(0, cur)) return;
;     f32x4 acc[2][2][4][2];
; #pragma unroll
;     for (int a = 0; a < 2; ++a)
; #pragma unroll
;         for (int b = 0; b < 2; ++b)
; #pragma unroll
;             for (int m = 0; m < 4; ++m)
; #pragma unroll
;                 for (int n = 0; n < 2; ++n) acc[a][b][m][n] = (f32x4){0.f, 0.f, 0.f, 0.f};
;     bf16x8 At[4][2], B0[2][2], B1[2][2];
;     const char* cA = (const char*)g.A + (size_t)cur.pm * tstep; const char* cB = (const char*)g.Bt + (size_t)cur.pn * tstep;
;     S.a_ready(cur);
;     if constexpr (SP2) {
;         PG8_STAGE(PG8_SB(0, 0), cB, voffB); PG8_STAGE(PG8_SB(0, 1), cB + hstep, voffB); PG8_STAGE(PG8_SA(0, 0), cA, voffA); PG8_STAGE(PG8_SA(0, 1), cA + hstep, voffA);
;         if (wr == 1) PG8_BAR;
;         PG8_WAIT_V(2); PG8_BAR;
;         PG8_STAGE(PG8_SB(1, 0), cB + kstep, voffB); PG8_STAGE(PG8_SA(1, 0), cA + kstep, voffA); PG8_STAGE(PG8_SB(1, 1), cB + hstep + kstep, voffB);
;         PG8_WAIT_V(6); PG8_BAR;
.LBB0_1332:
	s_cmp_lt_i32 s30, 16
	s_cselect_b64 s[4:5], -1, 0
	s_and_b64 s[4:5], s[4:5], s[0:1]
	s_andn2_b64 vcc, exec, s[4:5]
	s_cbranch_vccnz .LBB0_1349
	s_cmpk_gt_i32 s2, 0x15ff
	v_readfirstlane_b32 s1, v152
	s_cbranch_scc1 .LBB0_1349
	s_waitcnt vmcnt(0)
	v_lshrrev_b32_e32 v2, 1, v152
	v_and_b32_e32 v11, 24, v2
	v_lshrrev_b32_e32 v2, 5, v152
	v_and_b32_e32 v2, 4, v2
	v_bfe_u32 v3, v152, 2, 2
	v_lshlrev_b32_e32 v0, 4, v152
	v_and_b32_e32 v1, 32, v152
	v_bfe_u32 v10, v152, 2, 4
	v_or3_b32 v2, v2, v3, v11
	v_lshrrev_b32_e32 v3, 3, v152
	s_movk_i32 s0, 0x70
	v_bitop3_b32 v8, v0, v1, 48 bitop3:0x6c
	v_and_b32_e32 v9, 64, v152
	v_and_or_b32 v4, v3, s0, v10
	s_movk_i32 s0, 0x60
	v_add_u32_e32 v12, 0x2000, v0
	s_add_u32 s42, s28, 0x1600000
	v_or_b32_e32 v1, v8, v9
	v_and_or_b32 v3, v3, s0, v2
	v_lshrrev_b32_e32 v0, 7, v12
	s_movk_i32 s0, 0xf0
	s_addc_u32 s43, s29, 0
	v_lshl_or_b32 v130, v3, 11, v1
	v_and_or_b32 v3, v0, s0, v10
	s_movk_i32 s0, 0xe0
	s_ashr_i32 s45, s2, 31
	v_and_or_b32 v0, v0, s0, v2
	s_lshr_b32 s0, s45, 29
	s_add_i32 s0, s2, s0
	s_lshr_b32 s10, s1, 6
	s_ashr_i32 s6, s0, 3
	s_and_b32 s0, s0, -8
	s_lshr_b32 s12, s1, 8
	s_lshl_b32 s44, s10, 10
	s_sub_i32 s0, s2, s0
	s_cmp_lt_i32 s0, 0
	s_movk_i32 s46, 0x2c1
	s_cselect_b32 s7, s46, 0x2c0
	s_mul_i32 s0, s0, s7
	s_add_i32 s0, s0, s6
	s_mul_hi_i32 s6, s0, 0x2e8ba2e9
	s_lshr_b32 s7, s6, 31
	s_ashr_i32 s6, s6, 5
	s_add_i32 s6, s6, s7
	s_lshl_b32 s7, s6, 3
	s_mulk_i32 s6, 0xb0
	s_sub_i32 s6, s0, s6
	s_sext_i32_i16 s0, s6
	s_bfe_u32 s0, s0, 0x3001c
	s_add_i32 s8, s6, s0
	s_sext_i32_i16 s0, s8
	s_and_b32 s8, s8, 0xfff8
	s_sub_i32 s6, s6, s8
	s_sext_i32_i16 s6, s6
	s_lshr_b32 s0, s0, 3
	s_add_i32 s24, s7, s6
	s_ashr_i32 s25, s24, 31
	s_bfe_i64 s[8:9], s[0:1], 0x100000
	s_lshl_b64 s[6:7], s[24:25], 19
	s_lshl_b64 s[8:9], s[8:9], 19
	s_add_u32 s38, s42, s8
	s_addc_u32 s39, s43, s9
	s_add_i32 s25, s44, 0
	s_add_i32 m0, s25, 0x10000
	v_lshl_or_b32 v134, v0, 11, v1
	global_load_lds_dwordx4 v130, s[38:39]
	s_add_i32 m0, s25, 0x12000
	s_add_u32 s8, s38, 0x40000
	global_load_lds_dwordx4 v134, s[38:39]
	s_addc_u32 s9, s39, 0
	s_add_i32 m0, s25, 0x14000
	v_lshl_or_b32 v128, v4, 11, v1
	global_load_lds_dwordx4 v130, s[8:9]
	s_add_i32 m0, s25, 0x16000
	s_add_u32 s36, s16, s6
	s_addc_u32 s37, s17, s7
	s_add_i32 s47, s25, 0x2000
	global_load_lds_dwordx4 v134, s[8:9]
	s_mov_b32 m0, s25
	s_add_u32 s6, s36, 0x40000
	v_lshl_or_b32 v132, v3, 11, v1
	global_load_lds_dwordx4 v128, s[36:37]
	s_mov_b32 m0, s47
	s_addc_u32 s7, s37, 0
	s_add_i32 s48, s25, 0x4000
	global_load_lds_dwordx4 v132, s[36:37]
	s_mov_b32 m0, s48
	s_add_i32 s49, s25, 0x6000
	global_load_lds_dwordx4 v128, s[6:7]
	s_mov_b32 m0, s49
	v_mov_b32_e32 v131, 0
	global_load_lds_dwordx4 v132, s[6:7]
	v_mov_b32_e32 v135, v131
	v_mov_b32_e32 v129, v131
	v_mov_b32_e32 v133, v131
	s_cmp_eq_u32 s12, 1
	s_mov_b32 s50, 0
	v_lshl_add_u64 v[6:7], s[38:39], 0, v[130:131]
	v_lshl_add_u64 v[4:5], s[38:39], 0, v[134:135]
	v_lshl_add_u64 v[0:1], s[36:37], 0, v[128:129]
	s_cselect_b64 s[6:7], -1, 0
	s_cmp_lg_u32 s12, 1
	v_lshl_add_u64 v[2:3], s[36:37], 0, v[132:133]
	s_add_u32 s8, s28, 0xfa00000
	s_addc_u32 s9, s29, 0
	s_lshl_b32 s10, s10, 5
	s_and_b32 s18, s10, 0x60
	s_mov_b64 s[10:11], 0x80
	s_add_i32 m0, s25, 0x18000
	v_lshl_add_u64 v[6:7], v[6:7], 0, s[10:11]
	s_ashr_i32 s51, s3, 31
	s_lshl_b32 s13, s12, 13
	s_lshl_b32 s19, s18, 7
	global_load_lds_dwordx4 v[6:7], off
	v_lshl_add_u64 v[4:5], v[4:5], 0, s[10:11]
	s_add_i32 m0, s25, 0x1a000
	s_add_i32 s52, s25, 0x8000
	s_add_i32 s53, s25, 0xa000
	global_load_lds_dwordx4 v[4:5], off
	v_lshl_add_u64 v[0:1], v[0:1], 0, s[10:11]
	s_mov_b32 m0, s52
	s_add_u32 s14, s38, 0x40080
	global_load_lds_dwordx4 v[0:1], off
	v_lshl_add_u64 v[0:1], v[2:3], 0, s[10:11]
	s_mov_b32 m0, s53
	s_addc_u32 s15, s39, 0
	global_load_lds_dwordx4 v[0:1], off
	s_add_i32 m0, s25, 0x1c000
	v_lshl_add_u64 v[0:1], s[14:15], 0, v[130:131]
	global_load_lds_dwordx4 v[0:1], off
	v_lshl_add_u64 v[0:1], s[14:15], 0, v[134:135]
	s_add_i32 m0, s25, 0x1e000
	s_sext_i32_i16 s57, s0
	global_load_lds_dwordx4 v[0:1], off
	s_cmp_lg_u32 s12, 1
	s_cbranch_scc1 .LBB0_1336
	s_barrier
.LBB0_1336:
	s_waitcnt vmcnt(8)
	s_barrier
	v_and_b32_e32 v0, 15, v152
	v_lshlrev_b32_e32 v1, 1, v11
	v_lshlrev_b32_e32 v2, 6, v152
	s_movk_i32 s0, 0x3c0
	v_lshlrev_b32_e32 v3, 2, v152
	v_and_or_b32 v2, v2, s0, v1
	v_and_b32_e32 v3, 32, v3
	v_lshl_or_b32 v144, s12, 6, v0
	v_lshl_or_b32 v0, v0, 6, v1
	v_lshlrev_b32_e32 v1, 8, v152
	v_bitop3_b32 v145, s19, v2, v3 bitop3:0xf6
	v_and_b32_e32 v1, 0x38000, v1
	v_lshlrev_b32_e32 v2, 11, v10
	v_or3_b32 v1, v8, v1, v2
	v_add_u32_e32 v136, v1, v9
	v_lshlrev_b32_e32 v1, 4, v12
	s_waitcnt vmcnt(6)
	s_cmpk_lt_u32 s1, 0x100
	v_and_b32_e32 v1, 0x78000, v1
	v_bitop3_b32 v0, v0, s13, v3 bitop3:0xde
	s_cselect_b64 s[12:13], -1, 0
	v_or3_b32 v1, v8, v1, v2
	s_add_i32 s54, 0, 0x10000
	s_add_i32 s55, 0, 0x14000
	v_or_b32_e32 v146, s18, v11
	v_mov_b32_e32 v137, v131
	v_add_u32_e32 v138, v1, v9
	v_mov_b32_e32 v139, v131
	v_mov_b64_e32 v[140:141], 0x1600
	v_mov_b64_e32 v[142:143], 0x15ff
	v_add_u32_e32 v147, s54, v145
	v_add_u32_e32 v148, s55, v145
	v_add_u32_e32 v149, 0, v0
	s_movk_i32 s56, 0x1600
	s_barrier
	s_mov_b32 s77, 0
	s_branch .LBB0_1339

;     __host__ __device__ bool next(int i, Unit& u) const {
;         const long L = (long)i * G + c; if (L >= nwg) return false;
;         int wgid = (int)L; { const int q = nwg / NXCD, r = nwg % NXCD, xcd = wgid % NXCD, off = wgid / NXCD; wgid = (xcd < r ? xcd * (q + 1) : r * (q + 1) + (xcd - r) * q) + off; }
;         const int nig = WGM * nN, gid = wgid / nig, fm = gid * WGM, gsz = (nM - fm) < WGM ? (nM - fm) : WGM;
; template <class Epi, class Sched, bool ALIGN_EPI = false, bool SP2 = false>
; __device__ __forceinline__ void gemm_phase(PG8_LAS unsigned char* lds, const Gemm g, const Sched& S, const Epi& E) {
;     const int tid = threadIdx.x, wid = __builtin_amdgcn_readfirstlane(tid >> 6), lane = tid & 63, wr = wid >> 2, wc = wid & 3, fr = lane & 15, fq = lane >> 4;
;     const int K = g.K, nt = K / BK;
;     unsigned voffA[2], voffB[2];
; #pragma unroll
;     for (int i = 0; i < 2; ++i) { int R, C; stage_rc(tid * 16 + i * 8192, R, C); const int Rb = Epi::PERM ? ((R & ~31) + perm32(R & 31)) : R;
;         voffA[i] = (unsigned)(R * K + C) * 2u; voffB[i] = (unsigned)(Rb * K + C) * 2u; }
;     const size_t kstep = (size_t)(BK * 2);
;     const size_t hstep = (size_t)HALF * K * 2;
;     const size_t tstep = 2 * hstep;
;     const unsigned ldsw = (unsigned)wid * 1024u;
;     const int aoff = lds_byte(wr * 64 + fr, fq * 8), boff = lds_byte(wc * 32 + fr, fq * 8);
;     ...
;     Unit cur, nxt; int ui = 0;
;     if (!S.next(0, cur)) return;
;     f32x4 acc[2][2][4][2];
; #pragma unroll
;     for (int a = 0; a < 2; ++a)
; #pragma unroll
;         for (int b = 0; b < 2; ++b)
; #pragma unroll
;             for (int m = 0; m < 4; ++m)
; #pragma unroll
;                 for (int n = 0; n < 2; ++n) acc[a][b][m][n] = (f32x4){0.f, 0.f, 0.f, 0.f};
;     bf16x8 At[4][2], B0[2][2], B1[2][2];
;     const char* cA = (const char*)g.A + (size_t)cur.pm * tstep; const char* cB = (const char*)g.Bt + (size_t)cur.pn * tstep;
;     S.a_ready(cur);
;     if constexpr (SP2) {
;         PG8_STAGE(PG8_SB(0, 0), cB, voffB); PG8_STAGE(PG8_SB(0, 1), cB + hstep, voffB); PG8_STAGE(PG8_SA(0, 0), cA, voffA); PG8_STAGE(PG8_SA(0, 1), cA + hstep, voffA);
;         if (wr == 1) PG8_BAR;
;         PG8_WAIT_V(2); PG8_BAR;
;         PG8_STAGE(PG8_SB(1, 0), cB + kstep, voffB); PG8_STAGE(PG8_SA(1, 0), cA + kstep, voffA); PG8_STAGE(PG8_SB(1, 1), cB + hstep + kstep, voffB);
;         PG8_WAIT_V(6); PG8_BAR;
.LBB0_1399:
	s_cmp_lt_i32 s30, 17
	s_cselect_b64 s[4:5], -1, 0
	s_and_b64 s[0:1], s[4:5], s[0:1]
	s_andn2_b64 vcc, exec, s[0:1]
	s_cbranch_vccnz .LBB0_1424
	s_cmpk_gt_i32 s2, 0x3ff
	v_readfirstlane_b32 s0, v152
	s_cbranch_scc1 .LBB0_1424
	s_add_u32 s33, s28, 0xfa00000
	s_addc_u32 s34, s29, 0
	s_waitcnt vmcnt(0)
	v_lshrrev_b32_e32 v3, 1, v152
	s_add_u32 s35, s28, 0x2700000
	v_and_b32_e32 v10, 24, v3
	v_lshrrev_b32_e32 v3, 5, v152
	s_addc_u32 s36, s29, 0
	v_and_b32_e32 v3, 4, v3
	v_bfe_u32 v4, v152, 2, 2
	s_ashr_i32 s38, s2, 31
	v_lshlrev_b32_e32 v0, 4, v152
	v_and_b32_e32 v1, 32, v152
	v_bfe_u32 v2, v152, 2, 4
	v_or3_b32 v3, v3, v4, v10
	v_lshrrev_b32_e32 v4, 3, v152
	s_movk_i32 s1, 0x70
	s_lshr_b32 s4, s38, 29
	v_bitop3_b32 v8, v0, v1, 48 bitop3:0x6c
	v_and_or_b32 v5, v4, s1, v2
	s_movk_i32 s1, 0x60
	v_add_u32_e32 v0, 0x2000, v0
	s_add_i32 s4, s2, s4
	v_and_or_b32 v4, v4, s1, v3
	v_lshrrev_b32_e32 v0, 7, v0
	s_movk_i32 s1, 0xf0
	s_ashr_i32 s6, s4, 3
	s_and_b32 s4, s4, -8
	v_and_or_b32 v2, v0, s1, v2
	s_movk_i32 s1, 0xe0
	s_lshr_b32 s5, s0, 6
	s_sub_i32 s4, s2, s4
	v_and_or_b32 v0, v0, s1, v3
	s_lshr_b32 s1, s0, 8
	s_lshl_b32 s37, s5, 10
	s_lshl_b32 s8, s4, 7
	s_mul_i32 s7, s4, 0x81
	s_cmp_lt_i32 s4, 0
	s_cselect_b32 s4, s7, s8
	s_add_i32 s4, s4, s6
	s_ashr_i32 s6, s4, 31
	s_lshr_b32 s6, s6, 27
	s_add_i32 s6, s4, s6
	s_ashr_i32 s7, s6, 5
	s_and_b32 s6, s6, 0xffe0
	s_sub_i32 s6, s4, s6
	s_bfe_i32 s4, s6, 0x80000
	s_bfe_u32 s4, s4, 0x3000c
	s_add_i32 s8, s6, s4
	s_bfe_i32 s4, s8, 0x80000
	s_and_b32 s8, s8, 0xf8
	s_sub_i32 s6, s6, s8
	s_lshl_b32 s7, s7, 3
	s_sext_i32_i16 s9, s4
	s_sext_i32_i8 s6, s6
	v_and_b32_e32 v9, 64, v152
	s_add_i32 s53, s7, s6
	s_ashr_i32 s6, s9, 3
	v_or_b32_e32 v1, v8, v9
	s_lshr_b32 s4, s9, 3
	s_mul_hi_i32 s7, s6, 0x160000
	s_mul_i32 s6, s6, 0x160000
	v_lshrrev_b32_e32 v1, 1, v1
	v_mul_u32_u24_e32 v4, 0xb00, v4
	s_add_u32 s30, s35, s6
	v_or_b32_e32 v4, v4, v1
	s_addc_u32 s31, s36, s7
	s_add_i32 s39, s37, 0
	v_lshlrev_b32_e32 v138, 1, v4
	v_mul_u32_u24_e32 v0, 0xb00, v0
	s_add_i32 m0, s39, 0x10000
	v_or_b32_e32 v0, v0, v1
	global_load_lds_dwordx4 v138, s[30:31]
	s_add_i32 m0, s39, 0x12000
	v_lshlrev_b32_e32 v142, 1, v0
	s_add_u32 s6, s30, 0xb0000
	global_load_lds_dwordx4 v142, s[30:31]
	s_addc_u32 s7, s31, 0
	s_add_i32 m0, s39, 0x14000
	s_mul_i32 s10, s53, 0x160000
	global_load_lds_dwordx4 v138, s[6:7]
	s_add_i32 m0, s39, 0x16000
	v_mul_u32_u24_e32 v11, 0xb00, v5
	s_mul_hi_i32 s8, s53, 0x160000
	s_add_u32 s24, s33, s10
	v_or_b32_e32 v5, v1, v11
	v_mul_u32_u24_e32 v12, 0xb00, v2
	s_addc_u32 s25, s34, s8
	s_add_i32 s40, s39, 0x2000
	v_lshlrev_b32_e32 v136, 1, v5
	v_or_b32_e32 v2, v12, v1
	global_load_lds_dwordx4 v142, s[6:7]
	s_mov_b32 m0, s39
	s_add_u32 s6, s24, 0xb0000
	v_lshlrev_b32_e32 v140, 1, v2
	global_load_lds_dwordx4 v136, s[24:25]
	s_mov_b32 m0, s40
	s_addc_u32 s7, s25, 0
	s_add_i32 s41, s39, 0x4000
	global_load_lds_dwordx4 v140, s[24:25]
	s_mov_b32 m0, s41
	s_add_i32 s42, s39, 0x6000
	global_load_lds_dwordx4 v136, s[6:7]
	s_mov_b32 m0, s42
	v_mov_b32_e32 v139, 0
	global_load_lds_dwordx4 v140, s[6:7]
	v_mov_b32_e32 v143, v139
	v_mov_b32_e32 v137, v139
	v_mov_b32_e32 v141, v139
	s_cmp_eq_u32 s1, 1
	s_mov_b32 s43, 0
	v_lshl_add_u64 v[6:7], s[30:31], 0, v[138:139]
	v_lshl_add_u64 v[4:5], s[30:31], 0, v[142:143]
	v_lshl_add_u64 v[0:1], s[24:25], 0, v[136:137]
	s_cselect_b64 s[6:7], -1, 0
	s_cmp_lg_u32 s1, 1
	v_lshl_add_u64 v[2:3], s[24:25], 0, v[140:141]
	s_add_u32 s8, s28, 0x2fa00000
	s_addc_u32 s9, s29, 0
	s_add_u32 s44, s28, 0x3b000
	s_addc_u32 s45, s29, 0
	s_lshl_b32 s5, s5, 5
	s_mov_b64 s[10:11], 0x80
	s_and_b32 s5, s5, 0x60
	s_add_i32 m0, s39, 0x18000
	v_lshl_add_u64 v[6:7], v[6:7], 0, s[10:11]
	s_ashr_i32 s46, s3, 31
	s_lshl_b32 s14, s1, 13
	s_lshl_b32 s15, s5, 7
	global_load_lds_dwordx4 v[6:7], off
	v_lshl_add_u64 v[4:5], v[4:5], 0, s[10:11]
	s_add_i32 m0, s39, 0x1a000
	s_add_i32 s47, s39, 0x8000
	s_add_i32 s48, s39, 0xa000
	global_load_lds_dwordx4 v[4:5], off
	v_lshl_add_u64 v[0:1], v[0:1], 0, s[10:11]
	s_mov_b32 m0, s47
	s_add_u32 s12, s30, 0xb0080
	global_load_lds_dwordx4 v[0:1], off
	v_lshl_add_u64 v[0:1], v[2:3], 0, s[10:11]
	s_mov_b32 m0, s48
	s_addc_u32 s13, s31, 0
	global_load_lds_dwordx4 v[0:1], off
	s_add_i32 m0, s39, 0x1c000
	v_lshl_add_u64 v[0:1], s[12:13], 0, v[138:139]
	global_load_lds_dwordx4 v[0:1], off
	v_lshl_add_u64 v[0:1], s[12:13], 0, v[142:143]
	s_add_i32 m0, s39, 0x1e000
	s_sext_i32_i8 s54, s4
	global_load_lds_dwordx4 v[0:1], off
	s_cmp_lg_u32 s1, 1
	s_cbranch_scc1 .LBB0_1403
	s_barrier
.LBB0_1403:
	s_waitcnt vmcnt(8)
	s_barrier
	v_and_b32_e32 v0, 15, v152
	v_lshlrev_b32_e32 v1, 1, v10
	v_lshlrev_b32_e32 v2, 6, v152
	s_movk_i32 s4, 0x3c0
	v_lshlrev_b32_e32 v3, 2, v152
	v_and_or_b32 v2, v2, s4, v1
	v_and_b32_e32 v3, 32, v3
	v_lshl_or_b32 v158, s1, 6, v0
	v_lshl_or_b32 v0, v0, 6, v1
	s_waitcnt vmcnt(6)
	s_cmpk_lt_u32 s0, 0x100
	v_add_u16_e32 v1, v8, v9
	v_bitop3_b32 v0, v0, s14, v3 bitop3:0xde
	v_bitop3_b32 v159, s15, v2, v3 bitop3:0xf6
	s_cselect_b64 s[12:13], -1, 0
	v_lshrrev_b16_e32 v1, 1, v1
	s_add_i32 s49, 0, 0x10000
	s_add_i32 s50, 0, 0x14000
	v_or_b32_e32 v160, s5, v10
	v_add_lshl_u32 v144, v11, v1, 1
	v_mov_b32_e32 v145, v139
	v_add_lshl_u32 v146, v12, v1, 1
	v_mov_b32_e32 v147, v139
	v_mov_b64_e32 v[148:149], 0x400
	v_mov_b64_e32 v[150:151], 0x3ff
	v_add_u32_e32 v161, s49, v159
	v_add_u32_e32 v162, s50, v159
	v_add_u32_e32 v163, 0, v0
	s_mov_b64 s[14:15], 0x20000
	s_mov_b64 s[16:17], 0x24000
	s_mov_b64 s[18:19], 0x28000
	s_mov_b64 s[20:21], 0x2c000
	s_barrier
	s_branch .LBB0_1406
